# wave-specialised producer/consumer GEMM core now also for RES phases 8,11,16,19 (split-K tail via f32 atomics, residual+bf16+sumsq epilogue)
# speedup vs baseline: 1.0473x; 1.0473x over previous
; #define PH(n, sync_) if (plo <= (n) && (n) <= phi) { if ((n) > plo && (sync_)) { if ((n) == 1) { grid.sync(); xb = xcd_barrier_post((unsigned*)(ws + O_XBAR), (volatile LAS unsigned*)&xb_words); } else xcd_barrier(xb); }
; __global__ void __launch_bounds__(512) mega(Params p, int plo, int phi) {
;     ...
;   PH(8, 1) gemm_phase<EPI_RES>(p, WSB(O_Y), 1024, WSB(O_WOUT0), 1024, 1024, 1024, WSO(O_XB), 1024, 1, 0); PHEND
.LBB0_1087:
	s_mov_b32 s101, 8
	s_branch .Lgm_entry

; #define PH(n, sync_) if (plo <= (n) && (n) <= phi) { if ((n) > plo && (sync_)) { if ((n) == 1) { grid.sync(); xb = xcd_barrier_post((unsigned*)(ws + O_XBAR), (volatile LAS unsigned*)&xb_words); } else xcd_barrier(xb); }
; __global__ void __launch_bounds__(512) mega(Params p, int plo, int phi) {
;     ...
;   PH(1, 1) gemm_phase<EPI_SCALE>(p, WSB(O_XB), 1024, WSB(O_WIN0), 1024, 1024, 2816, WSO(O_P), 2816, 0, 0); PHEND
;   PH(2, 1) pool_phase(p); PHEND
;   PH(3, 1) gemm_phase<EPI_PLAIN>(p, WSB(O_LIN), 256, WSB(O_WLW), 64, 64, 768, WSO(O_WPRE), 768, 0, 0); PHEND
;   PH(4, 0) gemm_phase<EPI_PLAIN>(p, WSB(O_LIN + 128), 256, WSB(O_WLA), 64, 64, 768, WSO(O_APRE), 768, 0, 140); PHEND
;   PH(5, 1) rwkv_prep_phase(p); PHEND
;   PH(6, 1) scan_phase(p, 0, 0, 3264); pool_queue(p); PHEND
;   PH(7, 1) gemm_phase<EPI_POST>(p, WSB(O_LIN + 256), 256, WSB(O_WLG), 128, 128, 768, nullptr, 0, 0, 0); PHEND
;   PH(8, 1) gemm_phase<EPI_RES>(p, WSB(O_Y), 1024, WSB(O_WOUT0), 1024, 1024, 1024, WSO(O_XB), 1024, 1, 0); PHEND
;   PH(9, 1) res_fix_phase(p); PHEND
;   PH(10, 1) gemm_phase<EPI_FF1>(p, WSB(O_XB), 1024, WSB(O_WF10), 1024, 1024, 4096, WSO(O_H), 4096, 0, 0); PHEND
;   PH(11, 1) gemm_phase<EPI_RES>(p, WSB(O_H), 4096, WSB(O_WF20), 4096, 4096, 1024, WSO(O_XB), 1024, 0, 0); PHEND
;   PH(12, 1) res_fix_phase(p); PHEND
;   PH(13, 1) gemm_phase<EPI_SCALE>(p, WSB(O_XB), 1024, WSB(O_WIN1), 1024, 1024, 2048, WSO(O_P), 2048, 0, 0); PHEND
;   PH(14, 1) mix1_phase(p); PHEND
;   PH(15, 1) lru_fix_phase(p, xb); PHEND
;   PH(16, 1) gemm_phase<EPI_RES>(p, WSB(O_Y), 1024, WSB(O_WOUT1), 1024, 1024, 1024, WSO(O_XB), 1024, 0, 0); PHEND
;   PH(17, 1) res_fix_phase(p); PHEND
;   PH(18, 1) gemm_phase<EPI_FF1>(p, WSB(O_XB), 1024, WSB(O_WF11), 1024, 1024, 4096, WSO(O_H), 4096, 0, 0); PHEND
;   PH(19, 1) gemm_phase<EPI_RES>(p, WSB(O_H), 4096, WSB(O_WF21), 4096, 4096, 1024, WSO(O_XB), 1024, 0, 0); PHEND
.Lgm_entry:
	v_writelane_b32 v255, s0, 0
	v_writelane_b32 v255, s1, 1
	v_writelane_b32 v255, s2, 2
	v_writelane_b32 v255, s3, 3
	v_writelane_b32 v255, s4, 4
	v_writelane_b32 v255, s5, 5
	v_writelane_b32 v255, s18, 6
	v_writelane_b32 v255, s19, 7
	v_writelane_b32 v255, s20, 8
	v_writelane_b32 v255, s21, 9
	v_writelane_b32 v255, s22, 10
	v_writelane_b32 v255, s23, 11
	v_writelane_b32 v255, s24, 12
	v_writelane_b32 v255, s25, 13
	v_writelane_b32 v255, s26, 14
	v_writelane_b32 v255, s27, 15
	v_writelane_b32 v255, s28, 16
	v_writelane_b32 v255, s29, 17
	v_writelane_b32 v255, s30, 18
	v_writelane_b32 v255, s31, 19
	v_writelane_b32 v255, s32, 20
	v_writelane_b32 v255, s33, 21
	v_writelane_b32 v255, s34, 22
	v_writelane_b32 v255, s35, 23
	v_writelane_b32 v255, s36, 24
	v_writelane_b32 v255, s37, 25
	v_writelane_b32 v255, s38, 26
	v_writelane_b32 v255, s39, 27
	v_writelane_b32 v255, s44, 28
	v_writelane_b32 v255, s45, 29
	v_writelane_b32 v255, s46, 30
	v_writelane_b32 v255, s47, 31
	v_writelane_b32 v255, s48, 32
	v_writelane_b32 v255, s49, 33
.Lgm_entry_nosave:
	s_cmp_eq_u32 s101, 1
	s_cbranch_scc1 .Lgm_par1
	s_cmp_eq_u32 s101, 8
	s_cbranch_scc1 .Lgm_par8
	s_cmp_eq_u32 s101, 10
	s_cbranch_scc1 .Lgm_par10
	s_cmp_eq_u32 s101, 11
	s_cbranch_scc1 .Lgm_par11
	s_cmp_eq_u32 s101, 13
	s_cbranch_scc1 .Lgm_par13
	s_cmp_eq_u32 s101, 16
	s_cbranch_scc1 .Lgm_par16
	s_cmp_eq_u32 s101, 18
	s_cbranch_scc1 .Lgm_par18
	s_cmp_eq_u32 s101, 19
	s_cbranch_scc1 .Lgm_par19
	s_branch .Lgm_par19
.Lgm_par1:
	s_add_u32 s16, s96, 0x2f08100
	s_addc_u32 s17, s97, 0
	s_add_u32 s20, s96, 0x0
	s_addc_u32 s21, s97, 0
	s_add_u32 s22, s96, 0x7108100
	s_addc_u32 s23, s97, 0
	s_movk_i32 s24, 0x1600
	s_mov_b32 s25, 22
	s_mov_b32 s26, 0xba2e8bb
	s_mov_b32 s27, 0
	s_movk_i32 s28, 0x5ac
	s_movk_i32 s29, 0x500
	s_mov_b32 s30, 0
	s_movk_i32 s38, 0x5ac
	s_mov_b32 s39, 16
	s_mov_b32 s44, 0
	s_mov_b32 s45, 11
	s_mov_b32 s46, 11
	s_branch .Lgm_common
.Lgm_par8:
	s_add_u32 s16, s96, 0x5008100
	s_addc_u32 s17, s97, 0
	s_add_u32 s20, s96, 0x580000
	s_addc_u32 s21, s97, 0
	s_add_u32 s22, s96, 0x2f08100
	s_addc_u32 s23, s97, 0
	s_movk_i32 s24, 0x800
	s_mov_b32 s25, 8
	s_mov_b32 s26, 0x20000000
	s_mov_b32 s27, 3
	s_movk_i32 s28, 0x200
	s_movk_i32 s29, 0x200
	s_mov_b32 s30, 3
	s_movk_i32 s38, 0x240
	s_mov_b32 s39, 16
	s_mov_b32 s44, 2
	s_mov_b32 s45, 11
	s_mov_b32 s46, 11
	s_mov_b32 s48, s60
	s_mov_b32 s49, s61
	s_branch .Lgm_common
.Lgm_par10:
	s_add_u32 s16, s96, 0x2f08100
	s_addc_u32 s17, s97, 0
	s_add_u32 s20, s96, 0x780000
	s_addc_u32 s21, s97, 0
	s_add_u32 s22, s96, 0x7108100
	s_addc_u32 s23, s97, 0
	s_movk_i32 s24, 0x2000
	s_mov_b32 s25, 32
	s_mov_b32 s26, 0x8000000
	s_mov_b32 s27, 1
	s_movk_i32 s28, 0x840
	s_movk_i32 s29, 0x800
	s_mov_b32 s30, 1
	s_movk_i32 s38, 0x840
	s_mov_b32 s39, 16
	s_mov_b32 s44, 0
	s_mov_b32 s45, 11
	s_mov_b32 s46, 11
	s_branch .Lgm_common
.Lgm_par11:
	s_add_u32 s16, s96, 0x7108100
	s_addc_u32 s17, s97, 0
	s_add_u32 s20, s96, 0xf80000
	s_addc_u32 s21, s97, 0
	s_add_u32 s22, s96, 0x2f08100
	s_addc_u32 s23, s97, 0
	s_movk_i32 s24, 0x800
	s_mov_b32 s25, 8
	s_mov_b32 s26, 0x20000000
	s_mov_b32 s27, 3
	s_movk_i32 s28, 0x200
	s_movk_i32 s29, 0x200
	s_mov_b32 s30, 3
	s_movk_i32 s38, 0x280
	s_mov_b32 s39, 64
	s_mov_b32 s44, 3
	s_mov_b32 s45, 13
	s_mov_b32 s46, 13
	s_mov_b32 s48, s94
	s_mov_b32 s49, s95
	s_branch .Lgm_common
.Lgm_par13:
	s_add_u32 s16, s96, 0x2f08100
	s_addc_u32 s17, s97, 0
	s_add_u32 s20, s96, 0x1780000
	s_addc_u32 s21, s97, 0
	s_add_u32 s22, s96, 0x7108100
	s_addc_u32 s23, s97, 0
	s_movk_i32 s24, 0x1000
	s_mov_b32 s25, 16
	s_mov_b32 s26, 0x10000000
	s_mov_b32 s27, 2
	s_movk_i32 s28, 0x420
	s_movk_i32 s29, 0x400
	s_mov_b32 s30, 0
	s_movk_i32 s38, 0x420
	s_mov_b32 s39, 16
	s_mov_b32 s44, 0
	s_mov_b32 s45, 11
	s_mov_b32 s46, 11
	s_branch .Lgm_common
.Lgm_par16:
	s_add_u32 s16, s96, 0x5008100
	s_addc_u32 s17, s97, 0
	s_add_u32 s20, s96, 0x1b80000
	s_addc_u32 s21, s97, 0
	s_add_u32 s22, s96, 0x2f08100
	s_addc_u32 s23, s97, 0
	s_movk_i32 s24, 0x800
	s_mov_b32 s25, 8
	s_mov_b32 s26, 0x20000000
	s_mov_b32 s27, 3
	s_movk_i32 s28, 0x200
	s_movk_i32 s29, 0x200
	s_mov_b32 s30, 3
	s_movk_i32 s38, 0x240
	s_mov_b32 s39, 16
	s_mov_b32 s44, 2
	s_mov_b32 s45, 11
	s_mov_b32 s46, 11
	s_mov_b32 s48, s94
	s_mov_b32 s49, s95
	s_branch .Lgm_common
.Lgm_par18:
	s_add_u32 s16, s96, 0x2f08100
	s_addc_u32 s17, s97, 0
	s_add_u32 s20, s96, 0x1d80000
	s_addc_u32 s21, s97, 0
	s_add_u32 s22, s96, 0x7108100
	s_addc_u32 s23, s97, 0
	s_movk_i32 s24, 0x2000
	s_mov_b32 s25, 32
	s_mov_b32 s26, 0x8000000
	s_mov_b32 s27, 1
	s_movk_i32 s28, 0x840
	s_movk_i32 s29, 0x800
	s_mov_b32 s30, 1
	s_movk_i32 s38, 0x840
	s_mov_b32 s39, 16
	s_mov_b32 s44, 0
	s_mov_b32 s45, 11
	s_mov_b32 s46, 11
	s_branch .Lgm_common
.Lgm_par19:
	s_add_u32 s16, s96, 0x7108100
	s_addc_u32 s17, s97, 0
	s_add_u32 s20, s96, 0x2580000
	s_addc_u32 s21, s97, 0
	s_add_u32 s22, s96, 0x2f08100
	s_addc_u32 s23, s97, 0
	s_movk_i32 s24, 0x800
	s_mov_b32 s25, 8
	s_mov_b32 s26, 0x20000000
	s_mov_b32 s27, 3
	s_movk_i32 s28, 0x200
	s_movk_i32 s29, 0x200
	s_mov_b32 s30, 3
	s_movk_i32 s38, 0x280
	s_mov_b32 s39, 64
	s_mov_b32 s44, 3
	s_mov_b32 s45, 13
	s_mov_b32 s46, 13
	s_mov_b32 s48, s94
	s_mov_b32 s49, s95
	s_branch .Lgm_common
; template <int EPI>
; __device__ __forceinline__ void gemm_phase(const Params& p, const u16* __restrict__ A, int lda, const u16* __restrict__ BT, int ldb,
;                            int K, int N, u16* __restrict__ outb, int ldo, int resid_in, int boff) {
;     ...
;   const int G = gridDim.x;
;   int t_full = tiles, split = 1;
;   if (EPI == EPI_RES) {
;     const int tail = tiles % G;
;     if (tail > 0 && (G % tail) == 0 && (KTALL % (G / tail)) == 0) { t_full = tiles - tail; const int smax = (KTALL >= 64) ? 8 : 4; split = (G / tail) > smax ? smax : (G / tail); }
;   }
;   const int units = t_full + (tiles - t_full) * split;
;   for (int un = bstart; un < units; un += G) {
;     int tl = un, kbeg = 0, KT = KTALL;
;     bool part_unit = false;
;     if (un >= t_full) { const int v = un - t_full; tl = t_full + v / split; KT = KTALL / split; kbeg = (v % split) * KT; part_unit = true; }
;     int mt = tl / NT, nt = tl % NT;
;     if (EPI == EPI_RES && NT == 8 && G == 256 && !part_unit) {
;       const int rr = tl >> 8, bb = tl & 255;
;       const int xx = bb & 7, jj = bb >> 3;
;       mt = rr * 32 + xx * 4 + (jj >> 3);
;       nt = jj & 7;
;     } else if ((EPI == EPI_FF1 || EPI == EPI_SCALE) && G == 256 && (NT == 32 || NT == 16) && tl < (tiles & ~255)) {
;       const int rr = tl >> 8, bb = tl & 255;
;       const int xx = bb & 7, jj = bb >> 3;
;       if (NT == 32) { mt = rr * 8 + (xx >> 2) * 4 + (jj >> 3); nt = (xx & 3) * 8 + (jj & 7); }
;       else { mt = rr * 16 + (xx >> 1) * 4 + (jj >> 3); nt = (xx & 1) * 8 + (jj & 7); }
;     }
;     const int m0 = mt * 256, n0 = nt * 128;
;     const u16* gA = A + (size_t)(m0 + lrow) * lda + lch * 8 + (size_t)kbeg * 64;
;     const u16* gB = BT + (size_t)(n0 + lrow) * ldb + lch * 8 + (size_t)kbeg * 64;
.Lgm_common:
	s_add_u32 s14, s96, 0x2e00100
	s_addc_u32 s15, s97, 0
	v_mov_b32_e32 v190, 0x1c040
	ds_read_b64 v[192:193], v190
	v_lshrrev_b32_e32 v191, 6, v128
	s_waitcnt lgkmcnt(0)
	v_readfirstlane_b32 s98, v192
	v_readfirstlane_b32 s99, v193
	v_readfirstlane_b32 s4, v191
	v_readlane_b32 s5, v254, 0
	s_nop 3
	s_cmp_ge_u32 s4, 4
	s_cbranch_scc1 .Lgm_producer
	v_and_b32_e32 v192, 63, v128
	v_lshrrev_b32_e32 v201, 5, v192
	v_and_b32_e32 v200, 31, v192
	v_bfe_u32 v190, v192, 1, 3
	v_lshlrev_b32_e32 v191, 7, v200
	s_lshl_b32 s8, s4, 13
	v_or_b32_e32 v193, 0, v201
	v_xor_b32_e32 v193, v193, v190
	v_lshlrev_b32_e32 v193, 4, v193
	v_add_u32_e32 v193, v193, v191
	v_add_u32_e32 v178, s8, v193
	v_add_u32_e32 v182, 0x8000, v193
	v_or_b32_e32 v193, 2, v201
	v_xor_b32_e32 v193, v193, v190
	v_lshlrev_b32_e32 v193, 4, v193
	v_add_u32_e32 v193, v193, v191
	v_add_u32_e32 v179, s8, v193
	v_add_u32_e32 v183, 0x8000, v193
	v_or_b32_e32 v193, 4, v201
	v_xor_b32_e32 v193, v193, v190
	v_lshlrev_b32_e32 v193, 4, v193
	v_add_u32_e32 v193, v193, v191
	v_add_u32_e32 v180, s8, v193
	v_add_u32_e32 v184, 0x8000, v193
	v_or_b32_e32 v193, 6, v201
	v_xor_b32_e32 v193, v193, v190
	v_lshlrev_b32_e32 v193, 4, v193
	v_add_u32_e32 v193, v193, v191
	v_add_u32_e32 v181, s8, v193
	v_add_u32_e32 v185, 0x8000, v193
	v_lshlrev_b32_e32 v194, 2, v200
	s_lshl_b32 s10, s4, 8
	s_add_u32 s10, s10, 0x24000
	v_add_u32_e32 v194, s10, v194
	s_mov_b32 s13, 0
	s_mov_b32 s31, 0xc000
	s_mov_b32 s35, 0xc000
	s_mov_b32 s34, 0xfffe8000
	s_mov_b32 s33, 0
	v_mov_b64_e32 v[0:1], 0
	v_mov_b64_e32 v[2:3], 0
	v_mov_b64_e32 v[4:5], 0
	v_mov_b64_e32 v[6:7], 0
	v_mov_b64_e32 v[8:9], 0
	v_mov_b64_e32 v[10:11], 0
	v_mov_b64_e32 v[12:13], 0
	v_mov_b64_e32 v[14:15], 0
	v_mov_b64_e32 v[16:17], 0
	v_mov_b64_e32 v[18:19], 0
	v_mov_b64_e32 v[20:21], 0
	v_mov_b64_e32 v[22:23], 0
	v_mov_b64_e32 v[24:25], 0
	v_mov_b64_e32 v[26:27], 0
	v_mov_b64_e32 v[28:29], 0
	v_mov_b64_e32 v[30:31], 0
	v_mov_b64_e32 v[32:33], 0
	v_mov_b64_e32 v[34:35], 0
	v_mov_b64_e32 v[36:37], 0
	v_mov_b64_e32 v[38:39], 0
	v_mov_b64_e32 v[40:41], 0
	v_mov_b64_e32 v[42:43], 0
	v_mov_b64_e32 v[44:45], 0
	v_mov_b64_e32 v[46:47], 0
	v_mov_b64_e32 v[48:49], 0
	v_mov_b64_e32 v[50:51], 0
	v_mov_b64_e32 v[52:53], 0
	v_mov_b64_e32 v[54:55], 0
	v_mov_b64_e32 v[56:57], 0
	v_mov_b64_e32 v[58:59], 0
	v_mov_b64_e32 v[60:61], 0
	v_mov_b64_e32 v[62:63], 0
	v_mov_b64_e32 v[64:65], 0
	v_mov_b64_e32 v[66:67], 0
	v_mov_b64_e32 v[68:69], 0
	v_mov_b64_e32 v[70:71], 0
	v_mov_b64_e32 v[72:73], 0
	v_mov_b64_e32 v[74:75], 0
	v_mov_b64_e32 v[76:77], 0
	v_mov_b64_e32 v[78:79], 0
	v_mov_b64_e32 v[80:81], 0
	v_mov_b64_e32 v[82:83], 0
	v_mov_b64_e32 v[84:85], 0
	v_mov_b64_e32 v[86:87], 0
	v_mov_b64_e32 v[88:89], 0
	v_mov_b64_e32 v[90:91], 0
	v_mov_b64_e32 v[92:93], 0
	v_mov_b64_e32 v[94:95], 0
	v_mov_b64_e32 v[96:97], 0
	v_mov_b64_e32 v[98:99], 0
	v_mov_b64_e32 v[100:101], 0
	v_mov_b64_e32 v[102:103], 0
	v_mov_b64_e32 v[104:105], 0
	v_mov_b64_e32 v[106:107], 0
	v_mov_b64_e32 v[108:109], 0
	v_mov_b64_e32 v[110:111], 0
	v_mov_b64_e32 v[112:113], 0
	v_mov_b64_e32 v[114:115], 0
	v_mov_b64_e32 v[116:117], 0
	v_mov_b64_e32 v[118:119], 0
	v_mov_b64_e32 v[120:121], 0
	v_mov_b64_e32 v[122:123], 0
	v_mov_b64_e32 v[124:125], 0
	v_mov_b64_e32 v[126:127], 0
	v_mov_b64_e32 v[154:155], 0
	v_mov_b64_e32 v[156:157], 0
	v_mov_b64_e32 v[158:159], 0
	v_mov_b64_e32 v[160:161], 0
	v_mov_b64_e32 v[162:163], 0
	v_mov_b64_e32 v[164:165], 0
	v_mov_b64_e32 v[166:167], 0
	v_mov_b64_e32 v[168:169], 0
	v_mov_b64_e32 v[170:171], 0
	v_mov_b64_e32 v[172:173], 0
	v_mov_b64_e32 v[174:175], 0
	v_mov_b64_e32 v[176:177], 0
	s_waitcnt lgkmcnt(0)
	s_barrier
.Lgc_unit:
	s_cmp_ge_u32 s5, s38
	s_cbranch_scc1 .Lgm_exit
	s_cmp_ge_u32 s5, s28
	s_cbranch_scc1 .Lgm_split_c
	s_mov_b32 s8, 0
	s_mov_b32 s9, s39
	s_mov_b32 s10, 0
	s_cmp_eq_u32 s27, 0
	s_cbranch_scc1 .Lgm_plain_c
	s_cmp_ge_u32 s5, s29
	s_cbranch_scc1 .Lgm_plain_c
	s_lshr_b32 s6, s5, 8
	s_and_b32 s7, s5, 0xff
	s_and_b32 s36, s7, 7
	s_lshr_b32 s37, s7, 3
	s_cmp_eq_u32 s27, 3
	s_cbranch_scc1 .Lgm_map8_c
	s_cmp_eq_u32 s27, 1
	s_cbranch_scc0 .Lgm_map16_c
	s_lshl_b32 s6, s6, 3
	s_lshr_b32 s7, s36, 2
	s_lshl_b32 s7, s7, 2
	s_add_u32 s6, s6, s7
	s_lshr_b32 s7, s37, 3
	s_add_u32 s6, s6, s7
	s_and_b32 s7, s36, 3
	s_lshl_b32 s7, s7, 3
	s_and_b32 s37, s37, 7
	s_add_u32 s7, s7, s37
	s_branch .Lgm_dec_done_c
.Lgm_map16_c:
	s_lshl_b32 s6, s6, 4
	s_lshr_b32 s7, s36, 1
	s_lshl_b32 s7, s7, 2
	s_add_u32 s6, s6, s7
	s_lshr_b32 s7, s37, 3
	s_add_u32 s6, s6, s7
	s_and_b32 s7, s36, 1
	s_lshl_b32 s7, s7, 3
	s_and_b32 s37, s37, 7
	s_add_u32 s7, s7, s37
	s_branch .Lgm_dec_done_c
.Lgm_map8_c:
	s_lshl_b32 s6, s6, 5
	s_lshl_b32 s7, s36, 2
	s_add_u32 s6, s6, s7
	s_lshr_b32 s7, s37, 3
	s_add_u32 s6, s6, s7
	s_and_b32 s7, s37, 7
	s_branch .Lgm_dec_done_c
.Lgm_plain_c:
	s_mul_hi_u32 s6, s5, s26
	s_mul_i32 s7, s6, s25
	s_sub_u32 s7, s5, s7
	s_branch .Lgm_dec_done_c
.Lgm_split_c:
	s_sub_u32 s36, s5, s28
	s_lshr_b32 s37, s36, s44
	s_lshl_b32 s10, s37, s44
	s_sub_u32 s36, s36, s10
	s_add_u32 s37, s37, s28
	s_lshr_b32 s6, s37, 3
	s_and_b32 s7, s37, 7
	s_lshr_b32 s9, s39, s44
	s_mul_i32 s8, s36, s9
	s_mov_b32 s10, 1
.Lgm_dec_done_c:
	s_mov_b32 s18, s9
	s_cmp_eq_u32 s10, 1
	s_cbranch_scc1 .Lgc_loopN
; #define RAW_BARRIER() do { asm volatile("s_waitcnt lgkmcnt(0)" ::: "memory"); __builtin_amdgcn_s_barrier(); asm volatile("" ::: "memory"); } while (0)
; template <int EPI>
; __device__ __forceinline__ void gemm_phase(const Params& p, const u16* __restrict__ A, int lda, const u16* __restrict__ BT, int ldb,
;                            int K, int N, u16* __restrict__ outb, int ldo, int resid_in, int boff) {
;     ...
;     for (int kt = 0; kt < KT; kt += 2) {
;       if (kt + 1 < KT) WRITEY(1);
;       if (kt + 3 < KT) LOADY(kt + 3);
;       COMPUTE(0);
;       RAW_BARRIER();
;       if (kt + 1 >= KT) break;
;       if (kt + 2 < KT) WRITEX(0);
;       if (kt + 4 < KT) LOADX(kt + 4);
;       COMPUTE(1);
;       RAW_BARRIER();
;     }
.Lgc_loopT:
	ds_read_b128 v[130:133], v178
	ds_read_b128 v[138:141], v182
	ds_read_b128 v[142:145], v182 offset:4096
	ds_read_b128 v[134:137], v178 offset:4096
	ds_read_b128 v[146:149], v182 offset:8192
	ds_read_b128 v[150:153], v182 offset:12288
	v_mfma_f32_32x32x16_bf16 v[0:15], v[162:165], v[154:157], v[0:15]
	v_mfma_f32_32x32x16_bf16 v[16:31], v[166:169], v[154:157], v[16:31]
	v_mfma_f32_32x32x16_bf16 v[80:95], v[166:169], v[158:161], v[80:95]
	v_mfma_f32_32x32x16_bf16 v[64:79], v[162:165], v[158:161], v[64:79]
	v_mfma_f32_32x32x16_bf16 v[32:47], v[170:173], v[154:157], v[32:47]
	v_mfma_f32_32x32x16_bf16 v[48:63], v[174:177], v[154:157], v[48:63]
	v_mfma_f32_32x32x16_bf16 v[112:127], v[174:177], v[158:161], v[112:127]
	v_mfma_f32_32x32x16_bf16 v[96:111], v[170:173], v[158:161], v[96:111]
	ds_read_b128 v[154:157], v179
	ds_read_b128 v[162:165], v183
	ds_read_b128 v[166:169], v183 offset:4096
	ds_read_b128 v[158:161], v179 offset:4096
	ds_read_b128 v[170:173], v183 offset:8192
	ds_read_b128 v[174:177], v183 offset:12288
	s_waitcnt lgkmcnt(6)
	v_mfma_f32_32x32x16_bf16 v[0:15], v[138:141], v[130:133], v[0:15]
	v_mfma_f32_32x32x16_bf16 v[16:31], v[142:145], v[130:133], v[16:31]
	v_mfma_f32_32x32x16_bf16 v[80:95], v[142:145], v[134:137], v[80:95]
	v_mfma_f32_32x32x16_bf16 v[64:79], v[138:141], v[134:137], v[64:79]
	v_mfma_f32_32x32x16_bf16 v[32:47], v[146:149], v[130:133], v[32:47]
	v_mfma_f32_32x32x16_bf16 v[48:63], v[150:153], v[130:133], v[48:63]
	v_mfma_f32_32x32x16_bf16 v[112:127], v[150:153], v[134:137], v[112:127]
	v_mfma_f32_32x32x16_bf16 v[96:111], v[146:149], v[134:137], v[96:111]
	ds_read_b128 v[130:133], v180
	ds_read_b128 v[138:141], v184
	ds_read_b128 v[142:145], v184 offset:4096
	ds_read_b128 v[134:137], v180 offset:4096
	ds_read_b128 v[146:149], v184 offset:8192
	ds_read_b128 v[150:153], v184 offset:12288
	s_waitcnt lgkmcnt(6)
	v_mfma_f32_32x32x16_bf16 v[0:15], v[162:165], v[154:157], v[0:15]
	v_mfma_f32_32x32x16_bf16 v[16:31], v[166:169], v[154:157], v[16:31]
	v_mfma_f32_32x32x16_bf16 v[80:95], v[166:169], v[158:161], v[80:95]
	v_mfma_f32_32x32x16_bf16 v[64:79], v[162:165], v[158:161], v[64:79]
	v_mfma_f32_32x32x16_bf16 v[32:47], v[170:173], v[154:157], v[32:47]
	v_mfma_f32_32x32x16_bf16 v[48:63], v[174:177], v[154:157], v[48:63]
	v_mfma_f32_32x32x16_bf16 v[112:127], v[174:177], v[158:161], v[112:127]
	v_mfma_f32_32x32x16_bf16 v[96:111], v[170:173], v[158:161], v[96:111]
	ds_read_b128 v[154:157], v181
	ds_read_b128 v[162:165], v185
	ds_read_b128 v[166:169], v185 offset:4096
	ds_read_b128 v[158:161], v181 offset:4096
	ds_read_b128 v[170:173], v185 offset:8192
	ds_read_b128 v[174:177], v185 offset:12288
	s_waitcnt lgkmcnt(6)
	v_mfma_f32_32x32x16_bf16 v[0:15], v[138:141], v[130:133], v[0:15]
	v_add_u32_e32 v178, s31, v178
	v_mfma_f32_32x32x16_bf16 v[16:31], v[142:145], v[130:133], v[16:31]
	v_add_u32_e32 v179, s31, v179
	v_mfma_f32_32x32x16_bf16 v[80:95], v[142:145], v[134:137], v[80:95]
	v_add_u32_e32 v180, s31, v180
	v_mfma_f32_32x32x16_bf16 v[64:79], v[138:141], v[134:137], v[64:79]
	v_add_u32_e32 v181, s31, v181
	v_mfma_f32_32x32x16_bf16 v[32:47], v[146:149], v[130:133], v[32:47]
	v_add_u32_e32 v182, s31, v182
	v_mfma_f32_32x32x16_bf16 v[48:63], v[150:153], v[130:133], v[48:63]
	v_add_u32_e32 v183, s31, v183
	v_mfma_f32_32x32x16_bf16 v[112:127], v[150:153], v[134:137], v[112:127]
	v_add_u32_e32 v184, s31, v184
	v_mfma_f32_32x32x16_bf16 v[96:111], v[146:149], v[134:137], v[96:111]
	v_add_u32_e32 v185, s31, v185
	s_add_u32 s13, s13, 1
	s_cmp_eq_u32 s13, 3
	s_cselect_b32 s13, 0, s13
	s_cmp_eq_u32 s13, 2
	s_cselect_b32 s31, s34, s35
	s_waitcnt lgkmcnt(0)
	s_barrier
	s_sub_u32 s18, s18, 1
	s_cmp_lg_u32 s18, 0
	s_cbranch_scc1 .Lgc_loopT
	v_mfma_f32_32x32x16_bf16 v[0:15], v[162:165], v[154:157], v[0:15]
	v_mfma_f32_32x32x16_bf16 v[16:31], v[166:169], v[154:157], v[16:31]
	v_mfma_f32_32x32x16_bf16 v[80:95], v[166:169], v[158:161], v[80:95]
	v_mfma_f32_32x32x16_bf16 v[64:79], v[162:165], v[158:161], v[64:79]
	v_mfma_f32_32x32x16_bf16 v[32:47], v[170:173], v[154:157], v[32:47]
	v_mfma_f32_32x32x16_bf16 v[48:63], v[174:177], v[154:157], v[48:63]
	v_mfma_f32_32x32x16_bf16 v[112:127], v[174:177], v[158:161], v[112:127]
	v_mfma_f32_32x32x16_bf16 v[96:111], v[170:173], v[158:161], v[96:111]
	s_cmp_eq_u32 s30, 3
	s_cbranch_scc1 .Lgc_epi_res
; template <int EPI> ...
;     ...
;     if (EPI == EPI_SCALE || EPI == EPI_PLAIN || EPI == EPI_FF1) {
; #pragma unroll
;       for (int i = 0; i < 16; i++) {
;         const int rl = rbase + (i & 3) + 8 * (i >> 2);
;         const int row = m0 + rl;
;         float v0 = acc0[i], v1 = acc1[i];
;         if (EPI != EPI_PLAIN) { float rs = sRs[rl]; v0 *= rs; v1 *= rs; }
; template <int EPI>
; __device__ __forceinline__ void gemm_phase(const Params& p, const u16* __restrict__ A, int lda, const u16* __restrict__ BT, int ldb,
;                            int K, int N, u16* __restrict__ outb, int ldo, int resid_in, int boff) {
;     ...
;     if (EPI == EPI_SCALE || EPI == EPI_FF1) {
;       if (tid < 256) {
;         const float sq = (pq0.x + pq0.y + pq0.z + pq0.w) + (pq1.x + pq1.y + pq1.z + pq1.w) + (pq2.x + pq2.y + pq2.z + pq2.w) + (pq3.x + pq3.y + pq3.z + pq3.w);
;         sRs[tid] = rsqrtf(sq * (1.0f / 1024.0f) + 1e-6f);
;       }
;       __syncthreads();
;     }
;     const int c0 = n0 + wn * 64 + (lane & 31);
	s_lshl_b32 s11, s6, 8
	s_lshl_b32 s12, s4, 6
	s_add_u32 s11, s11, s12
	v_add_u32_e32 v190, s11, v200
	v_mul_lo_u32 v186, v190, s24
	s_lshl_b32 s11, s7, 7
	v_lshl_add_u32 v190, v201, 3, s11
	v_lshlrev_b32_e32 v190, 1, v190
	v_add_u32_e32 v186, v186, v190
	s_lshl_b32 s11, s24, 5
	v_add_u32_e32 v187, s11, v186
	s_nop 15
	v_add_u32_e32 v191, s33, v194
	ds_read_b32 v188, v191
	ds_read_b32 v189, v191 offset:128
	s_waitcnt lgkmcnt(0)
	v_mul_f32_e32 v0, v0, v188
	v_mul_f32_e32 v1, v1, v188
	v_mul_f32_e32 v2, v2, v188
	v_mul_f32_e32 v3, v3, v188
	v_mul_f32_e32 v4, v4, v188
	v_mul_f32_e32 v5, v5, v188
	v_mul_f32_e32 v6, v6, v188
	v_mul_f32_e32 v7, v7, v188
	v_mul_f32_e32 v8, v8, v188
	v_mul_f32_e32 v9, v9, v188
	v_mul_f32_e32 v10, v10, v188
	v_mul_f32_e32 v11, v11, v188
	v_mul_f32_e32 v12, v12, v188
	v_mul_f32_e32 v13, v13, v188
	v_mul_f32_e32 v14, v14, v188
	v_mul_f32_e32 v15, v15, v188
	v_mul_f32_e32 v16, v16, v188
	v_mul_f32_e32 v17, v17, v188
	v_mul_f32_e32 v18, v18, v188
	v_mul_f32_e32 v19, v19, v188
	v_mul_f32_e32 v20, v20, v188
	v_mul_f32_e32 v21, v21, v188
	v_mul_f32_e32 v22, v22, v188
	v_mul_f32_e32 v23, v23, v188
	v_mul_f32_e32 v24, v24, v188
	v_mul_f32_e32 v25, v25, v188
	v_mul_f32_e32 v26, v26, v188
	v_mul_f32_e32 v27, v27, v188
	v_mul_f32_e32 v28, v28, v188
	v_mul_f32_e32 v29, v29, v188
	v_mul_f32_e32 v30, v30, v188
	v_mul_f32_e32 v31, v31, v188
	v_mul_f32_e32 v32, v32, v188
	v_mul_f32_e32 v33, v33, v188
	v_mul_f32_e32 v34, v34, v188
	v_mul_f32_e32 v35, v35, v188
	v_mul_f32_e32 v36, v36, v188
	v_mul_f32_e32 v37, v37, v188
	v_mul_f32_e32 v38, v38, v188
	v_mul_f32_e32 v39, v39, v188
	v_mul_f32_e32 v40, v40, v188
	v_mul_f32_e32 v41, v41, v188
	v_mul_f32_e32 v42, v42, v188
	v_mul_f32_e32 v43, v43, v188
	v_mul_f32_e32 v44, v44, v188
	v_mul_f32_e32 v45, v45, v188
	v_mul_f32_e32 v46, v46, v188
	v_mul_f32_e32 v47, v47, v188
	v_mul_f32_e32 v48, v48, v188
	v_mul_f32_e32 v49, v49, v188
	v_mul_f32_e32 v50, v50, v188
	v_mul_f32_e32 v51, v51, v188
	v_mul_f32_e32 v52, v52, v188
	v_mul_f32_e32 v53, v53, v188
	v_mul_f32_e32 v54, v54, v188
	v_mul_f32_e32 v55, v55, v188
	v_mul_f32_e32 v56, v56, v188
	v_mul_f32_e32 v57, v57, v188
	v_mul_f32_e32 v58, v58, v188
	v_mul_f32_e32 v59, v59, v188
	v_mul_f32_e32 v60, v60, v188
	v_mul_f32_e32 v61, v61, v188
	v_mul_f32_e32 v62, v62, v188
	v_mul_f32_e32 v63, v63, v188
	v_mul_f32_e32 v64, v64, v189
	v_mul_f32_e32 v65, v65, v189
	v_mul_f32_e32 v66, v66, v189
	v_mul_f32_e32 v67, v67, v189
	v_mul_f32_e32 v68, v68, v189
	v_mul_f32_e32 v69, v69, v189
	v_mul_f32_e32 v70, v70, v189
	v_mul_f32_e32 v71, v71, v189
	v_mul_f32_e32 v72, v72, v189
	v_mul_f32_e32 v73, v73, v189
	v_mul_f32_e32 v74, v74, v189
	v_mul_f32_e32 v75, v75, v189
	v_mul_f32_e32 v76, v76, v189
	v_mul_f32_e32 v77, v77, v189
	v_mul_f32_e32 v78, v78, v189
	v_mul_f32_e32 v79, v79, v189
	v_mul_f32_e32 v80, v80, v189
	v_mul_f32_e32 v81, v81, v189
	v_mul_f32_e32 v82, v82, v189
	v_mul_f32_e32 v83, v83, v189
	v_mul_f32_e32 v84, v84, v189
	v_mul_f32_e32 v85, v85, v189
	v_mul_f32_e32 v86, v86, v189
	v_mul_f32_e32 v87, v87, v189
	v_mul_f32_e32 v88, v88, v189
	v_mul_f32_e32 v89, v89, v189
	v_mul_f32_e32 v90, v90, v189
	v_mul_f32_e32 v91, v91, v189
	v_mul_f32_e32 v92, v92, v189
	v_mul_f32_e32 v93, v93, v189
	v_mul_f32_e32 v94, v94, v189
	v_mul_f32_e32 v95, v95, v189
	v_mul_f32_e32 v96, v96, v189
	v_mul_f32_e32 v97, v97, v189
	v_mul_f32_e32 v98, v98, v189
	v_mul_f32_e32 v99, v99, v189
	v_mul_f32_e32 v100, v100, v189
	v_mul_f32_e32 v101, v101, v189
	v_mul_f32_e32 v102, v102, v189
	v_mul_f32_e32 v103, v103, v189
	v_mul_f32_e32 v104, v104, v189
	v_mul_f32_e32 v105, v105, v189
	v_mul_f32_e32 v106, v106, v189
	v_mul_f32_e32 v107, v107, v189
	v_mul_f32_e32 v108, v108, v189
	v_mul_f32_e32 v109, v109, v189
	v_mul_f32_e32 v110, v110, v189
	v_mul_f32_e32 v111, v111, v189
	v_mul_f32_e32 v112, v112, v189
	v_mul_f32_e32 v113, v113, v189
	v_mul_f32_e32 v114, v114, v189
	v_mul_f32_e32 v115, v115, v189
	v_mul_f32_e32 v116, v116, v189
	v_mul_f32_e32 v117, v117, v189
	v_mul_f32_e32 v118, v118, v189
	v_mul_f32_e32 v119, v119, v189
	v_mul_f32_e32 v120, v120, v189
	v_mul_f32_e32 v121, v121, v189
	v_mul_f32_e32 v122, v122, v189
	v_mul_f32_e32 v123, v123, v189
	v_mul_f32_e32 v124, v124, v189
	v_mul_f32_e32 v125, v125, v189
	v_mul_f32_e32 v126, v126, v189
	v_mul_f32_e32 v127, v127, v189
	s_cmp_eq_u32 s30, 0
	s_cbranch_scc1 .Lgm_norelu
; template <int EPI> ...
;     ...
;     if (EPI == EPI_SCALE || EPI == EPI_PLAIN || EPI == EPI_FF1) {
; #pragma unroll
;       for (int i = 0; i < 16; i++) {
;         const int rl = rbase + (i & 3) + 8 * (i >> 2);
;         const int row = m0 + rl;
;         float v0 = acc0[i], v1 = acc1[i];
;         if (EPI != EPI_PLAIN) { float rs = sRs[rl]; v0 *= rs; v1 *= rs; }
;         if (EPI == EPI_FF1) { v0 = fmaxf(v0, 0.f); v1 = fmaxf(v1, 0.f); v0 *= v0; v1 *= v1; }
;         outb[(size_t)row * ldo + c0] = f2bf(v0);
;         outb[(size_t)row * ldo + c1] = f2bf(v1);
;       }
	v_max_f32_e32 v0, 0, v0
	v_mul_f32_e32 v0, v0, v0
	v_max_f32_e32 v1, 0, v1
	v_mul_f32_e32 v1, v1, v1
	v_max_f32_e32 v2, 0, v2
	v_mul_f32_e32 v2, v2, v2
	v_max_f32_e32 v3, 0, v3
	v_mul_f32_e32 v3, v3, v3
	v_max_f32_e32 v4, 0, v4
	v_mul_f32_e32 v4, v4, v4
	v_max_f32_e32 v5, 0, v5
	v_mul_f32_e32 v5, v5, v5
	v_max_f32_e32 v6, 0, v6
	v_mul_f32_e32 v6, v6, v6
	v_max_f32_e32 v7, 0, v7
	v_mul_f32_e32 v7, v7, v7
	v_max_f32_e32 v8, 0, v8
	v_mul_f32_e32 v8, v8, v8
	v_max_f32_e32 v9, 0, v9
	v_mul_f32_e32 v9, v9, v9
	v_max_f32_e32 v10, 0, v10
	v_mul_f32_e32 v10, v10, v10
	v_max_f32_e32 v11, 0, v11
	v_mul_f32_e32 v11, v11, v11
	v_max_f32_e32 v12, 0, v12
	v_mul_f32_e32 v12, v12, v12
	v_max_f32_e32 v13, 0, v13
	v_mul_f32_e32 v13, v13, v13
	v_max_f32_e32 v14, 0, v14
	v_mul_f32_e32 v14, v14, v14
	v_max_f32_e32 v15, 0, v15
	v_mul_f32_e32 v15, v15, v15
	v_max_f32_e32 v16, 0, v16
	v_mul_f32_e32 v16, v16, v16
	v_max_f32_e32 v17, 0, v17
	v_mul_f32_e32 v17, v17, v17
	v_max_f32_e32 v18, 0, v18
	v_mul_f32_e32 v18, v18, v18
	v_max_f32_e32 v19, 0, v19
	v_mul_f32_e32 v19, v19, v19
	v_max_f32_e32 v20, 0, v20
	v_mul_f32_e32 v20, v20, v20
	v_max_f32_e32 v21, 0, v21
	v_mul_f32_e32 v21, v21, v21
	v_max_f32_e32 v22, 0, v22
	v_mul_f32_e32 v22, v22, v22
	v_max_f32_e32 v23, 0, v23
	v_mul_f32_e32 v23, v23, v23
	v_max_f32_e32 v24, 0, v24
	v_mul_f32_e32 v24, v24, v24
	v_max_f32_e32 v25, 0, v25
	v_mul_f32_e32 v25, v25, v25
	v_max_f32_e32 v26, 0, v26
	v_mul_f32_e32 v26, v26, v26
	v_max_f32_e32 v27, 0, v27
	v_mul_f32_e32 v27, v27, v27
	v_max_f32_e32 v28, 0, v28
	v_mul_f32_e32 v28, v28, v28
	v_max_f32_e32 v29, 0, v29
	v_mul_f32_e32 v29, v29, v29
	v_max_f32_e32 v30, 0, v30
	v_mul_f32_e32 v30, v30, v30
	v_max_f32_e32 v31, 0, v31
	v_mul_f32_e32 v31, v31, v31
	v_max_f32_e32 v32, 0, v32
	v_mul_f32_e32 v32, v32, v32
	v_max_f32_e32 v33, 0, v33
	v_mul_f32_e32 v33, v33, v33
	v_max_f32_e32 v34, 0, v34
	v_mul_f32_e32 v34, v34, v34
	v_max_f32_e32 v35, 0, v35
	v_mul_f32_e32 v35, v35, v35
	v_max_f32_e32 v36, 0, v36
	v_mul_f32_e32 v36, v36, v36
	v_max_f32_e32 v37, 0, v37
	v_mul_f32_e32 v37, v37, v37
	v_max_f32_e32 v38, 0, v38
	v_mul_f32_e32 v38, v38, v38
	v_max_f32_e32 v39, 0, v39
	v_mul_f32_e32 v39, v39, v39
	v_max_f32_e32 v40, 0, v40
	v_mul_f32_e32 v40, v40, v40
	v_max_f32_e32 v41, 0, v41
	v_mul_f32_e32 v41, v41, v41
	v_max_f32_e32 v42, 0, v42
	v_mul_f32_e32 v42, v42, v42
	v_max_f32_e32 v43, 0, v43
	v_mul_f32_e32 v43, v43, v43
	v_max_f32_e32 v44, 0, v44
	v_mul_f32_e32 v44, v44, v44
	v_max_f32_e32 v45, 0, v45
	v_mul_f32_e32 v45, v45, v45
	v_max_f32_e32 v46, 0, v46
	v_mul_f32_e32 v46, v46, v46
	v_max_f32_e32 v47, 0, v47
	v_mul_f32_e32 v47, v47, v47
	v_max_f32_e32 v48, 0, v48
	v_mul_f32_e32 v48, v48, v48
	v_max_f32_e32 v49, 0, v49
	v_mul_f32_e32 v49, v49, v49
	v_max_f32_e32 v50, 0, v50
	v_mul_f32_e32 v50, v50, v50
	v_max_f32_e32 v51, 0, v51
	v_mul_f32_e32 v51, v51, v51
	v_max_f32_e32 v52, 0, v52
	v_mul_f32_e32 v52, v52, v52
	v_max_f32_e32 v53, 0, v53
	v_mul_f32_e32 v53, v53, v53
	v_max_f32_e32 v54, 0, v54
	v_mul_f32_e32 v54, v54, v54
	v_max_f32_e32 v55, 0, v55
	v_mul_f32_e32 v55, v55, v55
	v_max_f32_e32 v56, 0, v56
	v_mul_f32_e32 v56, v56, v56
	v_max_f32_e32 v57, 0, v57
	v_mul_f32_e32 v57, v57, v57
	v_max_f32_e32 v58, 0, v58
	v_mul_f32_e32 v58, v58, v58
	v_max_f32_e32 v59, 0, v59
	v_mul_f32_e32 v59, v59, v59
	v_max_f32_e32 v60, 0, v60
	v_mul_f32_e32 v60, v60, v60
	v_max_f32_e32 v61, 0, v61
	v_mul_f32_e32 v61, v61, v61
	v_max_f32_e32 v62, 0, v62
	v_mul_f32_e32 v62, v62, v62
	v_max_f32_e32 v63, 0, v63
	v_mul_f32_e32 v63, v63, v63
	v_max_f32_e32 v64, 0, v64
	v_mul_f32_e32 v64, v64, v64
	v_max_f32_e32 v65, 0, v65
	v_mul_f32_e32 v65, v65, v65
	v_max_f32_e32 v66, 0, v66
	v_mul_f32_e32 v66, v66, v66
	v_max_f32_e32 v67, 0, v67
	v_mul_f32_e32 v67, v67, v67
	v_max_f32_e32 v68, 0, v68
	v_mul_f32_e32 v68, v68, v68
	v_max_f32_e32 v69, 0, v69
	v_mul_f32_e32 v69, v69, v69
	v_max_f32_e32 v70, 0, v70
	v_mul_f32_e32 v70, v70, v70
	v_max_f32_e32 v71, 0, v71
	v_mul_f32_e32 v71, v71, v71
	v_max_f32_e32 v72, 0, v72
	v_mul_f32_e32 v72, v72, v72
	v_max_f32_e32 v73, 0, v73
	v_mul_f32_e32 v73, v73, v73
	v_max_f32_e32 v74, 0, v74
	v_mul_f32_e32 v74, v74, v74
	v_max_f32_e32 v75, 0, v75
	v_mul_f32_e32 v75, v75, v75
	v_max_f32_e32 v76, 0, v76
	v_mul_f32_e32 v76, v76, v76
	v_max_f32_e32 v77, 0, v77
	v_mul_f32_e32 v77, v77, v77
	v_max_f32_e32 v78, 0, v78
	v_mul_f32_e32 v78, v78, v78
	v_max_f32_e32 v79, 0, v79
	v_mul_f32_e32 v79, v79, v79
	v_max_f32_e32 v80, 0, v80
	v_mul_f32_e32 v80, v80, v80
	v_max_f32_e32 v81, 0, v81
	v_mul_f32_e32 v81, v81, v81
	v_max_f32_e32 v82, 0, v82
	v_mul_f32_e32 v82, v82, v82
	v_max_f32_e32 v83, 0, v83
	v_mul_f32_e32 v83, v83, v83
	v_max_f32_e32 v84, 0, v84
	v_mul_f32_e32 v84, v84, v84
	v_max_f32_e32 v85, 0, v85
	v_mul_f32_e32 v85, v85, v85
	v_max_f32_e32 v86, 0, v86
	v_mul_f32_e32 v86, v86, v86
	v_max_f32_e32 v87, 0, v87
	v_mul_f32_e32 v87, v87, v87
	v_max_f32_e32 v88, 0, v88
	v_mul_f32_e32 v88, v88, v88
	v_max_f32_e32 v89, 0, v89
	v_mul_f32_e32 v89, v89, v89
	v_max_f32_e32 v90, 0, v90
	v_mul_f32_e32 v90, v90, v90
	v_max_f32_e32 v91, 0, v91
	v_mul_f32_e32 v91, v91, v91
	v_max_f32_e32 v92, 0, v92
	v_mul_f32_e32 v92, v92, v92
	v_max_f32_e32 v93, 0, v93
	v_mul_f32_e32 v93, v93, v93
	v_max_f32_e32 v94, 0, v94
	v_mul_f32_e32 v94, v94, v94
	v_max_f32_e32 v95, 0, v95
	v_mul_f32_e32 v95, v95, v95
	v_max_f32_e32 v96, 0, v96
	v_mul_f32_e32 v96, v96, v96
	v_max_f32_e32 v97, 0, v97
	v_mul_f32_e32 v97, v97, v97
	v_max_f32_e32 v98, 0, v98
	v_mul_f32_e32 v98, v98, v98
	v_max_f32_e32 v99, 0, v99
	v_mul_f32_e32 v99, v99, v99
	v_max_f32_e32 v100, 0, v100
	v_mul_f32_e32 v100, v100, v100
	v_max_f32_e32 v101, 0, v101
; template <int EPI> ...
;     ...
;     if (EPI == EPI_SCALE || EPI == EPI_PLAIN || EPI == EPI_FF1) {
; #pragma unroll
;       for (int i = 0; i < 16; i++) {
;         const int rl = rbase + (i & 3) + 8 * (i >> 2);
;         const int row = m0 + rl;
;         float v0 = acc0[i], v1 = acc1[i];
;         if (EPI != EPI_PLAIN) { float rs = sRs[rl]; v0 *= rs; v1 *= rs; }
;         if (EPI == EPI_FF1) { v0 = fmaxf(v0, 0.f); v1 = fmaxf(v1, 0.f); v0 *= v0; v1 *= v1; }
;         outb[(size_t)row * ldo + c0] = f2bf(v0);
;         outb[(size_t)row * ldo + c1] = f2bf(v1);
;       }
	v_mul_f32_e32 v101, v101, v101
	v_max_f32_e32 v102, 0, v102
	v_mul_f32_e32 v102, v102, v102
	v_max_f32_e32 v103, 0, v103
	v_mul_f32_e32 v103, v103, v103
	v_max_f32_e32 v104, 0, v104
	v_mul_f32_e32 v104, v104, v104
	v_max_f32_e32 v105, 0, v105
	v_mul_f32_e32 v105, v105, v105
	v_max_f32_e32 v106, 0, v106
	v_mul_f32_e32 v106, v106, v106
	v_max_f32_e32 v107, 0, v107
	v_mul_f32_e32 v107, v107, v107
	v_max_f32_e32 v108, 0, v108
	v_mul_f32_e32 v108, v108, v108
	v_max_f32_e32 v109, 0, v109
	v_mul_f32_e32 v109, v109, v109
	v_max_f32_e32 v110, 0, v110
	v_mul_f32_e32 v110, v110, v110
	v_max_f32_e32 v111, 0, v111
	v_mul_f32_e32 v111, v111, v111
	v_max_f32_e32 v112, 0, v112
	v_mul_f32_e32 v112, v112, v112
	v_max_f32_e32 v113, 0, v113
	v_mul_f32_e32 v113, v113, v113
	v_max_f32_e32 v114, 0, v114
	v_mul_f32_e32 v114, v114, v114
	v_max_f32_e32 v115, 0, v115
	v_mul_f32_e32 v115, v115, v115
	v_max_f32_e32 v116, 0, v116
	v_mul_f32_e32 v116, v116, v116
	v_max_f32_e32 v117, 0, v117
	v_mul_f32_e32 v117, v117, v117
	v_max_f32_e32 v118, 0, v118
	v_mul_f32_e32 v118, v118, v118
	v_max_f32_e32 v119, 0, v119
	v_mul_f32_e32 v119, v119, v119
	v_max_f32_e32 v120, 0, v120
	v_mul_f32_e32 v120, v120, v120
	v_max_f32_e32 v121, 0, v121
	v_mul_f32_e32 v121, v121, v121
	v_max_f32_e32 v122, 0, v122
	v_mul_f32_e32 v122, v122, v122
	v_max_f32_e32 v123, 0, v123
	v_mul_f32_e32 v123, v123, v123
	v_max_f32_e32 v124, 0, v124
	v_mul_f32_e32 v124, v124, v124
	v_max_f32_e32 v125, 0, v125
	v_mul_f32_e32 v125, v125, v125
	v_max_f32_e32 v126, 0, v126
	v_mul_f32_e32 v126, v126, v126
	v_max_f32_e32 v127, 0, v127
	v_mul_f32_e32 v127, v127, v127
.Lgm_norelu:
	v_cvt_pk_bf16_f32 v0, v0, v1
	v_cvt_pk_bf16_f32 v1, v2, v3
	v_cvt_pk_bf16_f32 v2, v4, v5
	v_cvt_pk_bf16_f32 v3, v6, v7
	v_cvt_pk_bf16_f32 v4, v8, v9
	v_cvt_pk_bf16_f32 v5, v10, v11
	v_cvt_pk_bf16_f32 v6, v12, v13
	v_cvt_pk_bf16_f32 v7, v14, v15
	s_nop 1
	v_permlane32_swap_b32_e32 v0, v2
	v_permlane32_swap_b32_e32 v1, v3
	v_permlane32_swap_b32_e32 v4, v6
	v_permlane32_swap_b32_e32 v5, v7
	global_store_dwordx4 v186, v[0:3], s[22:23]
	global_store_dwordx4 v186, v[4:7], s[22:23] offset:32
	v_cvt_pk_bf16_f32 v16, v16, v17
	v_cvt_pk_bf16_f32 v17, v18, v19
	v_cvt_pk_bf16_f32 v18, v20, v21
	v_cvt_pk_bf16_f32 v19, v22, v23
	v_cvt_pk_bf16_f32 v20, v24, v25
	v_cvt_pk_bf16_f32 v21, v26, v27
	v_cvt_pk_bf16_f32 v22, v28, v29
	v_cvt_pk_bf16_f32 v23, v30, v31
	s_nop 1
	v_permlane32_swap_b32_e32 v16, v18
	v_permlane32_swap_b32_e32 v17, v19
	v_permlane32_swap_b32_e32 v20, v22
	v_permlane32_swap_b32_e32 v21, v23
	global_store_dwordx4 v186, v[16:19], s[22:23] offset:64
	global_store_dwordx4 v186, v[20:23], s[22:23] offset:96
	v_cvt_pk_bf16_f32 v32, v32, v33
	v_cvt_pk_bf16_f32 v33, v34, v35
	v_cvt_pk_bf16_f32 v34, v36, v37
	v_cvt_pk_bf16_f32 v35, v38, v39
	v_cvt_pk_bf16_f32 v36, v40, v41
	v_cvt_pk_bf16_f32 v37, v42, v43
	v_cvt_pk_bf16_f32 v38, v44, v45
	v_cvt_pk_bf16_f32 v39, v46, v47
	s_nop 1
	v_permlane32_swap_b32_e32 v32, v34
	v_permlane32_swap_b32_e32 v33, v35
	v_permlane32_swap_b32_e32 v36, v38
	v_permlane32_swap_b32_e32 v37, v39
	global_store_dwordx4 v186, v[32:35], s[22:23] offset:128
	global_store_dwordx4 v186, v[36:39], s[22:23] offset:160
	v_cvt_pk_bf16_f32 v48, v48, v49
	v_cvt_pk_bf16_f32 v49, v50, v51
	v_cvt_pk_bf16_f32 v50, v52, v53
	v_cvt_pk_bf16_f32 v51, v54, v55
	v_cvt_pk_bf16_f32 v52, v56, v57
	v_cvt_pk_bf16_f32 v53, v58, v59
	v_cvt_pk_bf16_f32 v54, v60, v61
	v_cvt_pk_bf16_f32 v55, v62, v63
	s_nop 1
	v_permlane32_swap_b32_e32 v48, v50
	v_permlane32_swap_b32_e32 v49, v51
	v_permlane32_swap_b32_e32 v52, v54
	v_permlane32_swap_b32_e32 v53, v55
	global_store_dwordx4 v186, v[48:51], s[22:23] offset:192
	global_store_dwordx4 v186, v[52:55], s[22:23] offset:224
	v_cvt_pk_bf16_f32 v64, v64, v65
	v_cvt_pk_bf16_f32 v65, v66, v67
	v_cvt_pk_bf16_f32 v66, v68, v69
	v_cvt_pk_bf16_f32 v67, v70, v71
	v_cvt_pk_bf16_f32 v68, v72, v73
	v_cvt_pk_bf16_f32 v69, v74, v75
	v_cvt_pk_bf16_f32 v70, v76, v77
	v_cvt_pk_bf16_f32 v71, v78, v79
	s_nop 1
	v_permlane32_swap_b32_e32 v64, v66
	v_permlane32_swap_b32_e32 v65, v67
	v_permlane32_swap_b32_e32 v68, v70
	v_permlane32_swap_b32_e32 v69, v71
	global_store_dwordx4 v187, v[64:67], s[22:23]
	global_store_dwordx4 v187, v[68:71], s[22:23] offset:32
	v_cvt_pk_bf16_f32 v80, v80, v81
	v_cvt_pk_bf16_f32 v81, v82, v83
	v_cvt_pk_bf16_f32 v82, v84, v85
	v_cvt_pk_bf16_f32 v83, v86, v87
	v_cvt_pk_bf16_f32 v84, v88, v89
	v_cvt_pk_bf16_f32 v85, v90, v91
	v_cvt_pk_bf16_f32 v86, v92, v93
	v_cvt_pk_bf16_f32 v87, v94, v95
	s_nop 1
	v_permlane32_swap_b32_e32 v80, v82
	v_permlane32_swap_b32_e32 v81, v83
	v_permlane32_swap_b32_e32 v84, v86
	v_permlane32_swap_b32_e32 v85, v87
	global_store_dwordx4 v187, v[80:83], s[22:23] offset:64
	global_store_dwordx4 v187, v[84:87], s[22:23] offset:96
	v_cvt_pk_bf16_f32 v96, v96, v97
	v_cvt_pk_bf16_f32 v97, v98, v99
	v_cvt_pk_bf16_f32 v98, v100, v101
	v_cvt_pk_bf16_f32 v99, v102, v103
	v_cvt_pk_bf16_f32 v100, v104, v105
	v_cvt_pk_bf16_f32 v101, v106, v107
	v_cvt_pk_bf16_f32 v102, v108, v109
	v_cvt_pk_bf16_f32 v103, v110, v111
	s_nop 1
	v_permlane32_swap_b32_e32 v96, v98
	v_permlane32_swap_b32_e32 v97, v99
	v_permlane32_swap_b32_e32 v100, v102
	v_permlane32_swap_b32_e32 v101, v103
	global_store_dwordx4 v187, v[96:99], s[22:23] offset:128
	global_store_dwordx4 v187, v[100:103], s[22:23] offset:160
	v_cvt_pk_bf16_f32 v112, v112, v113
	v_cvt_pk_bf16_f32 v113, v114, v115
	v_cvt_pk_bf16_f32 v114, v116, v117
	v_cvt_pk_bf16_f32 v115, v118, v119
	v_cvt_pk_bf16_f32 v116, v120, v121
	v_cvt_pk_bf16_f32 v117, v122, v123
	v_cvt_pk_bf16_f32 v118, v124, v125
	v_cvt_pk_bf16_f32 v119, v126, v127
	s_nop 1
; template <int EPI> ...
;     ...
;     } else if (EPI == EPI_RES) {
; #pragma unroll
;       for (int i = 0; i < 16; i++) {
;         const int rl = rbase + (i & 3) + 8 * (i >> 2);
;         const int row = m0 + rl;
;         float v0 = acc0[i], v1 = acc1[i];
;         xf[(size_t)row * 1024 + c0] = v0;
;         xf[(size_t)row * 1024 + c1] = v1;
;         outb[(size_t)row * 1024 + c0] = f2bf(v0);
;         outb[(size_t)row * 1024 + c1] = f2bf(v1);
;         float s = hsum32(v0 * v0 + v1 * v1);
;         if ((lane & 31) == 0) part[(size_t)row * 16 + nt * 2 + wn] = s;
; template <int EPI>
; __device__ __forceinline__ void gemm_phase(const Params& p, const u16* __restrict__ A, int lda, const u16* __restrict__ BT, int ldb,
;                            int K, int N, u16* __restrict__ outb, int ldo, int resid_in, int boff) {
;     ...
;     if (EPI == EPI_RES && !part_unit) {
;       const int cc0 = n0 + wn * 64 + (lane & 31);
;       float* xfq = p.out;
; #pragma unroll
;       for (int i = 0; i < 16; i++) {
;         const int row = m0 + wm * 64 + 4 * (lane >> 5) + (i & 3) + 8 * (i >> 2);
;         const float* ra = resid_in ? xrow(p, row) : (xfq + (size_t)row * 1024);
;         const float* rb = resid_in ? xrow(p, row + 32) : (xfq + (size_t)(row + 32) * 1024);
;         acc00[i] = ra[cc0]; acc01[i] = ra[cc0 + 32];
;         acc10[i] = rb[cc0]; acc11[i] = rb[cc0 + 32];
;       }
	v_permlane32_swap_b32_e32 v112, v114
	v_permlane32_swap_b32_e32 v113, v115
	v_permlane32_swap_b32_e32 v116, v118
	v_permlane32_swap_b32_e32 v117, v119
	global_store_dwordx4 v187, v[112:115], s[22:23] offset:192
	global_store_dwordx4 v187, v[116:119], s[22:23] offset:224
	v_mov_b64_e32 v[8:9], 0
	v_mov_b64_e32 v[10:11], 0
	v_mov_b64_e32 v[12:13], 0
	v_mov_b64_e32 v[14:15], 0
	v_mov_b64_e32 v[24:25], 0
	v_mov_b64_e32 v[26:27], 0
	v_mov_b64_e32 v[28:29], 0
	v_mov_b64_e32 v[30:31], 0
	v_mov_b64_e32 v[40:41], 0
	v_mov_b64_e32 v[42:43], 0
	v_mov_b64_e32 v[44:45], 0
	v_mov_b64_e32 v[46:47], 0
	v_mov_b64_e32 v[56:57], 0
	v_mov_b64_e32 v[58:59], 0
	v_mov_b64_e32 v[60:61], 0
	v_mov_b64_e32 v[62:63], 0
	v_mov_b64_e32 v[72:73], 0
	v_mov_b64_e32 v[74:75], 0
	v_mov_b64_e32 v[76:77], 0
	v_mov_b64_e32 v[78:79], 0
	v_mov_b64_e32 v[88:89], 0
	v_mov_b64_e32 v[90:91], 0
	v_mov_b64_e32 v[92:93], 0
	v_mov_b64_e32 v[94:95], 0
	v_mov_b64_e32 v[104:105], 0
	v_mov_b64_e32 v[106:107], 0
	v_mov_b64_e32 v[108:109], 0
	v_mov_b64_e32 v[110:111], 0
	v_mov_b64_e32 v[120:121], 0
	v_mov_b64_e32 v[122:123], 0
	v_mov_b64_e32 v[124:125], 0
	v_mov_b64_e32 v[126:127], 0
	v_mov_b64_e32 v[154:155], 0
	v_mov_b64_e32 v[156:157], 0
	v_mov_b64_e32 v[158:159], 0
	v_mov_b64_e32 v[160:161], 0
	v_mov_b64_e32 v[162:163], 0
	v_mov_b64_e32 v[164:165], 0
	v_mov_b64_e32 v[166:167], 0
	v_mov_b64_e32 v[168:169], 0
	v_mov_b64_e32 v[170:171], 0
	v_mov_b64_e32 v[172:173], 0
	v_mov_b64_e32 v[174:175], 0
	v_mov_b64_e32 v[176:177], 0
	v_mov_b64_e32 v[0:1], 0
	v_mov_b64_e32 v[2:3], 0
	v_mov_b64_e32 v[4:5], 0
	v_mov_b64_e32 v[6:7], 0
	v_mov_b64_e32 v[16:17], 0
	v_mov_b64_e32 v[18:19], 0
	v_mov_b64_e32 v[20:21], 0
	v_mov_b64_e32 v[22:23], 0
	v_mov_b64_e32 v[32:33], 0
	v_mov_b64_e32 v[34:35], 0
	v_mov_b64_e32 v[36:37], 0
	v_mov_b64_e32 v[38:39], 0
	v_mov_b64_e32 v[48:49], 0
	v_mov_b64_e32 v[50:51], 0
	v_mov_b64_e32 v[52:53], 0
	v_mov_b64_e32 v[54:55], 0
	v_mov_b64_e32 v[64:65], 0
	v_mov_b64_e32 v[66:67], 0
	v_mov_b64_e32 v[68:69], 0
	v_mov_b64_e32 v[70:71], 0
	v_mov_b64_e32 v[80:81], 0
	v_mov_b64_e32 v[82:83], 0
	v_mov_b64_e32 v[84:85], 0
	v_mov_b64_e32 v[86:87], 0
	v_mov_b64_e32 v[96:97], 0
	v_mov_b64_e32 v[98:99], 0
	v_mov_b64_e32 v[100:101], 0
	v_mov_b64_e32 v[102:103], 0
	v_mov_b64_e32 v[112:113], 0
	v_mov_b64_e32 v[114:115], 0
	v_mov_b64_e32 v[116:117], 0
	v_mov_b64_e32 v[118:119], 0
	s_xor_b32 s33, s33, 0x400
	s_branch .Lgc_next
.Lgc_epi_res:
	s_lshl_b32 s11, s6, 8
	s_lshl_b32 s12, s4, 6
	s_add_u32 s11, s11, s12
	v_add_u32_e32 v190, s11, v200
	v_lshlrev_b32_e32 v195, 12, v190
	s_lshl_b32 s11, s7, 7
	v_lshl_add_u32 v191, v201, 2, s11
	v_lshlrev_b32_e32 v191, 2, v191
	v_add_u32_e32 v195, v195, v191
	v_add_u32_e32 v196, 0x20000, v195
	v_lshlrev_b32_e32 v197, 6, v190
	s_lshl_b32 s11, s7, 3
	v_add_u32_e32 v197, s11, v197
	s_lshl_b32 s11, s6, 8
	s_lshl_b32 s12, s4, 6
	s_add_u32 s11, s11, s12
	v_add_u32_e32 v190, s11, v200
	v_mul_lo_u32 v186, v190, s24
	s_lshl_b32 s11, s7, 7
	v_lshl_add_u32 v190, v201, 3, s11
	v_lshlrev_b32_e32 v190, 1, v190
	v_add_u32_e32 v186, v186, v190
	s_lshl_b32 s11, s24, 5
	v_add_u32_e32 v187, s11, v186
	global_load_dwordx4 v[130:133], v195, s[48:49] offset:0
	global_load_dwordx4 v[134:137], v195, s[48:49] offset:32
	global_load_dwordx4 v[138:141], v195, s[48:49] offset:64
	global_load_dwordx4 v[142:145], v195, s[48:49] offset:96
	global_load_dwordx4 v[146:149], v195, s[48:49] offset:128
	global_load_dwordx4 v[150:153], v195, s[48:49] offset:160
	global_load_dwordx4 v[154:157], v195, s[48:49] offset:192
	global_load_dwordx4 v[158:161], v195, s[48:49] offset:224
	global_load_dwordx4 v[162:165], v195, s[48:49] offset:256
	global_load_dwordx4 v[166:169], v195, s[48:49] offset:288
	global_load_dwordx4 v[170:173], v195, s[48:49] offset:320
	global_load_dwordx4 v[174:177], v195, s[48:49] offset:352
	s_nop 15
	s_waitcnt vmcnt(8)
	v_add_f32_e32 v0, v0, v130
	v_add_f32_e32 v1, v1, v131
	v_add_f32_e32 v2, v2, v132
	v_add_f32_e32 v3, v3, v133
	v_add_f32_e32 v4, v4, v134
	v_add_f32_e32 v5, v5, v135
	v_add_f32_e32 v6, v6, v136
	v_add_f32_e32 v7, v7, v137
	v_add_f32_e32 v8, v8, v138
	v_add_f32_e32 v9, v9, v139
	v_add_f32_e32 v10, v10, v140
	v_add_f32_e32 v11, v11, v141
	v_add_f32_e32 v12, v12, v142
	v_add_f32_e32 v13, v13, v143
	v_add_f32_e32 v14, v14, v144
	v_add_f32_e32 v15, v15, v145
	global_load_dwordx4 v[130:133], v195, s[48:49] offset:384
	global_load_dwordx4 v[134:137], v195, s[48:49] offset:416
	global_load_dwordx4 v[138:141], v195, s[48:49] offset:448
	global_load_dwordx4 v[142:145], v195, s[48:49] offset:480
	s_waitcnt vmcnt(8)
	v_add_f32_e32 v16, v16, v146
	v_add_f32_e32 v17, v17, v147
	v_add_f32_e32 v18, v18, v148
	v_add_f32_e32 v19, v19, v149
	v_add_f32_e32 v20, v20, v150
	v_add_f32_e32 v21, v21, v151
	v_add_f32_e32 v22, v22, v152
	v_add_f32_e32 v23, v23, v153
	v_add_f32_e32 v24, v24, v154
	v_add_f32_e32 v25, v25, v155
	v_add_f32_e32 v26, v26, v156
	v_add_f32_e32 v27, v27, v157
	v_add_f32_e32 v28, v28, v158
	v_add_f32_e32 v29, v29, v159
	v_add_f32_e32 v30, v30, v160
	v_add_f32_e32 v31, v31, v161
	global_load_dwordx4 v[146:149], v196, s[48:49] offset:0
	global_load_dwordx4 v[150:153], v196, s[48:49] offset:32
	global_load_dwordx4 v[154:157], v196, s[48:49] offset:64
	global_load_dwordx4 v[158:161], v196, s[48:49] offset:96
	s_waitcnt vmcnt(8)
; template <int EPI> ...
;     ...
;     } else if (EPI == EPI_RES) {
; #pragma unroll
;       for (int i = 0; i < 16; i++) {
;         const int rl = rbase + (i & 3) + 8 * (i >> 2);
;         const int row = m0 + rl;
;         float v0 = acc0[i], v1 = acc1[i];
;         xf[(size_t)row * 1024 + c0] = v0;
;         xf[(size_t)row * 1024 + c1] = v1;
;         outb[(size_t)row * 1024 + c0] = f2bf(v0);
;         outb[(size_t)row * 1024 + c1] = f2bf(v1);
;         float s = hsum32(v0 * v0 + v1 * v1);
;         if ((lane & 31) == 0) part[(size_t)row * 16 + nt * 2 + wn] = s;
; template <int EPI>
; __device__ __forceinline__ void gemm_phase(const Params& p, const u16* __restrict__ A, int lda, const u16* __restrict__ BT, int ldb,
;                            int K, int N, u16* __restrict__ outb, int ldo, int resid_in, int boff) {
;     ...
;       for (int i = 0; i < 16; i++) {
;         const int row = m0 + wm * 64 + 4 * (lane >> 5) + (i & 3) + 8 * (i >> 2);
;         const float* ra = resid_in ? xrow(p, row) : (xfq + (size_t)row * 1024);
;         const float* rb = resid_in ? xrow(p, row + 32) : (xfq + (size_t)(row + 32) * 1024);
;         acc00[i] = ra[cc0]; acc01[i] = ra[cc0 + 32];
;         acc10[i] = rb[cc0]; acc11[i] = rb[cc0 + 32];
;       }
	v_add_f32_e32 v32, v32, v162
	v_add_f32_e32 v33, v33, v163
	v_add_f32_e32 v34, v34, v164
	v_add_f32_e32 v35, v35, v165
	v_add_f32_e32 v36, v36, v166
	v_add_f32_e32 v37, v37, v167
	v_add_f32_e32 v38, v38, v168
	v_add_f32_e32 v39, v39, v169
	v_add_f32_e32 v40, v40, v170
	v_add_f32_e32 v41, v41, v171
	v_add_f32_e32 v42, v42, v172
	v_add_f32_e32 v43, v43, v173
	v_add_f32_e32 v44, v44, v174
	v_add_f32_e32 v45, v45, v175
	v_add_f32_e32 v46, v46, v176
	v_add_f32_e32 v47, v47, v177
	global_load_dwordx4 v[162:165], v196, s[48:49] offset:128
	global_load_dwordx4 v[166:169], v196, s[48:49] offset:160
	global_load_dwordx4 v[170:173], v196, s[48:49] offset:192
	global_load_dwordx4 v[174:177], v196, s[48:49] offset:224
	s_waitcnt vmcnt(8)
	v_add_f32_e32 v48, v48, v130
	v_add_f32_e32 v49, v49, v131
	v_add_f32_e32 v50, v50, v132
	v_add_f32_e32 v51, v51, v133
	v_add_f32_e32 v52, v52, v134
	v_add_f32_e32 v53, v53, v135
	v_add_f32_e32 v54, v54, v136
	v_add_f32_e32 v55, v55, v137
	v_add_f32_e32 v56, v56, v138
	v_add_f32_e32 v57, v57, v139
	v_add_f32_e32 v58, v58, v140
	v_add_f32_e32 v59, v59, v141
	v_add_f32_e32 v60, v60, v142
	v_add_f32_e32 v61, v61, v143
	v_add_f32_e32 v62, v62, v144
	v_add_f32_e32 v63, v63, v145
	global_load_dwordx4 v[130:133], v196, s[48:49] offset:256
	global_load_dwordx4 v[134:137], v196, s[48:49] offset:288
	global_load_dwordx4 v[138:141], v196, s[48:49] offset:320
	global_load_dwordx4 v[142:145], v196, s[48:49] offset:352
	s_waitcnt vmcnt(8)
	v_add_f32_e32 v64, v64, v146
	v_add_f32_e32 v65, v65, v147
	v_add_f32_e32 v66, v66, v148
	v_add_f32_e32 v67, v67, v149
	v_add_f32_e32 v68, v68, v150
	v_add_f32_e32 v69, v69, v151
	v_add_f32_e32 v70, v70, v152
	v_add_f32_e32 v71, v71, v153
	v_add_f32_e32 v72, v72, v154
	v_add_f32_e32 v73, v73, v155
	v_add_f32_e32 v74, v74, v156
	v_add_f32_e32 v75, v75, v157
	v_add_f32_e32 v76, v76, v158
	v_add_f32_e32 v77, v77, v159
	v_add_f32_e32 v78, v78, v160
	v_add_f32_e32 v79, v79, v161
	global_load_dwordx4 v[146:149], v196, s[48:49] offset:384
	global_load_dwordx4 v[150:153], v196, s[48:49] offset:416
	global_load_dwordx4 v[154:157], v196, s[48:49] offset:448
	global_load_dwordx4 v[158:161], v196, s[48:49] offset:480
	s_waitcnt vmcnt(8)
	v_add_f32_e32 v80, v80, v162
	v_add_f32_e32 v81, v81, v163
	v_add_f32_e32 v82, v82, v164
	v_add_f32_e32 v83, v83, v165
	v_add_f32_e32 v84, v84, v166
	v_add_f32_e32 v85, v85, v167
	v_add_f32_e32 v86, v86, v168
	v_add_f32_e32 v87, v87, v169
	v_add_f32_e32 v88, v88, v170
	v_add_f32_e32 v89, v89, v171
	v_add_f32_e32 v90, v90, v172
	v_add_f32_e32 v91, v91, v173
	v_add_f32_e32 v92, v92, v174
	v_add_f32_e32 v93, v93, v175
	v_add_f32_e32 v94, v94, v176
	v_add_f32_e32 v95, v95, v177
	s_waitcnt vmcnt(4)
	v_add_f32_e32 v96, v96, v130
	v_add_f32_e32 v97, v97, v131
	v_add_f32_e32 v98, v98, v132
	v_add_f32_e32 v99, v99, v133
	v_add_f32_e32 v100, v100, v134
	v_add_f32_e32 v101, v101, v135
	v_add_f32_e32 v102, v102, v136
	v_add_f32_e32 v103, v103, v137
	v_add_f32_e32 v104, v104, v138
	v_add_f32_e32 v105, v105, v139
	v_add_f32_e32 v106, v106, v140
	v_add_f32_e32 v107, v107, v141
	v_add_f32_e32 v108, v108, v142
	v_add_f32_e32 v109, v109, v143
	v_add_f32_e32 v110, v110, v144
	v_add_f32_e32 v111, v111, v145
	s_waitcnt vmcnt(0)
	v_add_f32_e32 v112, v112, v146
	v_add_f32_e32 v113, v113, v147
	v_add_f32_e32 v114, v114, v148
	v_add_f32_e32 v115, v115, v149
	v_add_f32_e32 v116, v116, v150
	v_add_f32_e32 v117, v117, v151
	v_add_f32_e32 v118, v118, v152
	v_add_f32_e32 v119, v119, v153
	v_add_f32_e32 v120, v120, v154
	v_add_f32_e32 v121, v121, v155
	v_add_f32_e32 v122, v122, v156
	v_add_f32_e32 v123, v123, v157
	v_add_f32_e32 v124, v124, v158
	v_add_f32_e32 v125, v125, v159
	v_add_f32_e32 v126, v126, v160
	v_add_f32_e32 v127, v127, v161
	global_store_dwordx4 v195, v[0:3], s[94:95] offset:0
	global_store_dwordx4 v195, v[4:7], s[94:95] offset:32
	global_store_dwordx4 v195, v[8:11], s[94:95] offset:64
	global_store_dwordx4 v195, v[12:15], s[94:95] offset:96
	v_mul_f32_e32 v198, v0, v0
	v_fmac_f32_e32 v198, v1, v1
	v_fmac_f32_e32 v198, v2, v2
	v_fmac_f32_e32 v198, v3, v3
	v_fmac_f32_e32 v198, v4, v4
	v_fmac_f32_e32 v198, v5, v5
	v_fmac_f32_e32 v198, v6, v6
	v_fmac_f32_e32 v198, v7, v7
	v_fmac_f32_e32 v198, v8, v8
	v_fmac_f32_e32 v198, v9, v9
	v_fmac_f32_e32 v198, v10, v10
	v_fmac_f32_e32 v198, v11, v11
	v_fmac_f32_e32 v198, v12, v12
	v_fmac_f32_e32 v198, v13, v13
	v_fmac_f32_e32 v198, v14, v14
	v_fmac_f32_e32 v198, v15, v15
	global_store_dwordx4 v195, v[16:19], s[94:95] offset:128
	global_store_dwordx4 v195, v[20:23], s[94:95] offset:160
	global_store_dwordx4 v195, v[24:27], s[94:95] offset:192
	global_store_dwordx4 v195, v[28:31], s[94:95] offset:224
	v_fmac_f32_e32 v198, v16, v16
	v_fmac_f32_e32 v198, v17, v17
	v_fmac_f32_e32 v198, v18, v18
	v_fmac_f32_e32 v198, v19, v19
	v_fmac_f32_e32 v198, v20, v20
	v_fmac_f32_e32 v198, v21, v21
	v_fmac_f32_e32 v198, v22, v22
	v_fmac_f32_e32 v198, v23, v23
	v_fmac_f32_e32 v198, v24, v24
	v_fmac_f32_e32 v198, v25, v25
	v_fmac_f32_e32 v198, v26, v26
	v_fmac_f32_e32 v198, v27, v27
	v_fmac_f32_e32 v198, v28, v28
	v_fmac_f32_e32 v198, v29, v29
	v_fmac_f32_e32 v198, v30, v30
	v_fmac_f32_e32 v198, v31, v31
	global_store_dwordx4 v195, v[32:35], s[94:95] offset:256
	global_store_dwordx4 v195, v[36:39], s[94:95] offset:288
	global_store_dwordx4 v195, v[40:43], s[94:95] offset:320
	global_store_dwordx4 v195, v[44:47], s[94:95] offset:352
	v_fmac_f32_e32 v198, v32, v32
	v_fmac_f32_e32 v198, v33, v33
	v_fmac_f32_e32 v198, v34, v34
	v_fmac_f32_e32 v198, v35, v35
	v_fmac_f32_e32 v198, v36, v36
	v_fmac_f32_e32 v198, v37, v37
	v_fmac_f32_e32 v198, v38, v38
	v_fmac_f32_e32 v198, v39, v39
; template <int EPI> ...
;     ...
;     } else if (EPI == EPI_RES) {
; #pragma unroll
;       for (int i = 0; i < 16; i++) {
;         const int rl = rbase + (i & 3) + 8 * (i >> 2);
;         const int row = m0 + rl;
;         float v0 = acc0[i], v1 = acc1[i];
;         xf[(size_t)row * 1024 + c0] = v0;
;         xf[(size_t)row * 1024 + c1] = v1;
;         outb[(size_t)row * 1024 + c0] = f2bf(v0);
;         outb[(size_t)row * 1024 + c1] = f2bf(v1);
;         float s = hsum32(v0 * v0 + v1 * v1);
;         if ((lane & 31) == 0) part[(size_t)row * 16 + nt * 2 + wn] = s;
	v_fmac_f32_e32 v198, v40, v40
	v_fmac_f32_e32 v198, v41, v41
	v_fmac_f32_e32 v198, v42, v42
	v_fmac_f32_e32 v198, v43, v43
	v_fmac_f32_e32 v198, v44, v44
	v_fmac_f32_e32 v198, v45, v45
	v_fmac_f32_e32 v198, v46, v46
	v_fmac_f32_e32 v198, v47, v47
	global_store_dwordx4 v195, v[48:51], s[94:95] offset:384
	global_store_dwordx4 v195, v[52:55], s[94:95] offset:416
	global_store_dwordx4 v195, v[56:59], s[94:95] offset:448
	global_store_dwordx4 v195, v[60:63], s[94:95] offset:480
	v_fmac_f32_e32 v198, v48, v48
	v_fmac_f32_e32 v198, v49, v49
	v_fmac_f32_e32 v198, v50, v50
	v_fmac_f32_e32 v198, v51, v51
	v_fmac_f32_e32 v198, v52, v52
	v_fmac_f32_e32 v198, v53, v53
	v_fmac_f32_e32 v198, v54, v54
	v_fmac_f32_e32 v198, v55, v55
	v_fmac_f32_e32 v198, v56, v56
	v_fmac_f32_e32 v198, v57, v57
	v_fmac_f32_e32 v198, v58, v58
	v_fmac_f32_e32 v198, v59, v59
	v_fmac_f32_e32 v198, v60, v60
	v_fmac_f32_e32 v198, v61, v61
	v_fmac_f32_e32 v198, v62, v62
	v_fmac_f32_e32 v198, v63, v63
	global_store_dwordx4 v196, v[64:67], s[94:95] offset:0
	global_store_dwordx4 v196, v[68:71], s[94:95] offset:32
	global_store_dwordx4 v196, v[72:75], s[94:95] offset:64
	global_store_dwordx4 v196, v[76:79], s[94:95] offset:96
	v_mul_f32_e32 v199, v64, v64
	v_fmac_f32_e32 v199, v65, v65
	v_fmac_f32_e32 v199, v66, v66
	v_fmac_f32_e32 v199, v67, v67
	v_fmac_f32_e32 v199, v68, v68
	v_fmac_f32_e32 v199, v69, v69
	v_fmac_f32_e32 v199, v70, v70
	v_fmac_f32_e32 v199, v71, v71
	v_fmac_f32_e32 v199, v72, v72
	v_fmac_f32_e32 v199, v73, v73
	v_fmac_f32_e32 v199, v74, v74
	v_fmac_f32_e32 v199, v75, v75
	v_fmac_f32_e32 v199, v76, v76
	v_fmac_f32_e32 v199, v77, v77
	v_fmac_f32_e32 v199, v78, v78
	v_fmac_f32_e32 v199, v79, v79
	global_store_dwordx4 v196, v[80:83], s[94:95] offset:128
	global_store_dwordx4 v196, v[84:87], s[94:95] offset:160
	global_store_dwordx4 v196, v[88:91], s[94:95] offset:192
	global_store_dwordx4 v196, v[92:95], s[94:95] offset:224
	v_fmac_f32_e32 v199, v80, v80
	v_fmac_f32_e32 v199, v81, v81
	v_fmac_f32_e32 v199, v82, v82
	v_fmac_f32_e32 v199, v83, v83
	v_fmac_f32_e32 v199, v84, v84
	v_fmac_f32_e32 v199, v85, v85
	v_fmac_f32_e32 v199, v86, v86
	v_fmac_f32_e32 v199, v87, v87
	v_fmac_f32_e32 v199, v88, v88
	v_fmac_f32_e32 v199, v89, v89
	v_fmac_f32_e32 v199, v90, v90
	v_fmac_f32_e32 v199, v91, v91
	v_fmac_f32_e32 v199, v92, v92
	v_fmac_f32_e32 v199, v93, v93
	v_fmac_f32_e32 v199, v94, v94
	v_fmac_f32_e32 v199, v95, v95
	global_store_dwordx4 v196, v[96:99], s[94:95] offset:256
	global_store_dwordx4 v196, v[100:103], s[94:95] offset:288
	global_store_dwordx4 v196, v[104:107], s[94:95] offset:320
	global_store_dwordx4 v196, v[108:111], s[94:95] offset:352
	v_fmac_f32_e32 v199, v96, v96
	v_fmac_f32_e32 v199, v97, v97
	v_fmac_f32_e32 v199, v98, v98
	v_fmac_f32_e32 v199, v99, v99
	v_fmac_f32_e32 v199, v100, v100
	v_fmac_f32_e32 v199, v101, v101
	v_fmac_f32_e32 v199, v102, v102
	v_fmac_f32_e32 v199, v103, v103
	v_fmac_f32_e32 v199, v104, v104
	v_fmac_f32_e32 v199, v105, v105
	v_fmac_f32_e32 v199, v106, v106
	v_fmac_f32_e32 v199, v107, v107
	v_fmac_f32_e32 v199, v108, v108
	v_fmac_f32_e32 v199, v109, v109
	v_fmac_f32_e32 v199, v110, v110
	v_fmac_f32_e32 v199, v111, v111
	global_store_dwordx4 v196, v[112:115], s[94:95] offset:384
	global_store_dwordx4 v196, v[116:119], s[94:95] offset:416
	global_store_dwordx4 v196, v[120:123], s[94:95] offset:448
	global_store_dwordx4 v196, v[124:127], s[94:95] offset:480
	v_fmac_f32_e32 v199, v112, v112
	v_fmac_f32_e32 v199, v113, v113
	v_fmac_f32_e32 v199, v114, v114
	v_fmac_f32_e32 v199, v115, v115
	v_fmac_f32_e32 v199, v116, v116
	v_fmac_f32_e32 v199, v117, v117
	v_fmac_f32_e32 v199, v118, v118
	v_fmac_f32_e32 v199, v119, v119
	v_fmac_f32_e32 v199, v120, v120
	v_fmac_f32_e32 v199, v121, v121
	v_fmac_f32_e32 v199, v122, v122
	v_fmac_f32_e32 v199, v123, v123
	v_fmac_f32_e32 v199, v124, v124
	v_fmac_f32_e32 v199, v125, v125
	v_fmac_f32_e32 v199, v126, v126
	v_fmac_f32_e32 v199, v127, v127
	v_cvt_pk_bf16_f32 v130, v0, v1
	v_cvt_pk_bf16_f32 v131, v2, v3
	v_cvt_pk_bf16_f32 v132, v4, v5
	v_cvt_pk_bf16_f32 v133, v6, v7
	v_cvt_pk_bf16_f32 v134, v8, v9
	v_cvt_pk_bf16_f32 v135, v10, v11
	v_cvt_pk_bf16_f32 v136, v12, v13
	v_cvt_pk_bf16_f32 v137, v14, v15
	s_nop 1
	v_permlane32_swap_b32_e32 v130, v132
	v_permlane32_swap_b32_e32 v131, v133
	v_permlane32_swap_b32_e32 v134, v136
	v_permlane32_swap_b32_e32 v135, v137
	global_store_dwordx4 v186, v[130:133], s[22:23]
	global_store_dwordx4 v186, v[134:137], s[22:23] offset:32
	v_cvt_pk_bf16_f32 v138, v16, v17
	v_cvt_pk_bf16_f32 v139, v18, v19
	v_cvt_pk_bf16_f32 v140, v20, v21
	v_cvt_pk_bf16_f32 v141, v22, v23
	v_cvt_pk_bf16_f32 v142, v24, v25
	v_cvt_pk_bf16_f32 v143, v26, v27
	v_cvt_pk_bf16_f32 v144, v28, v29
	v_cvt_pk_bf16_f32 v145, v30, v31
	s_nop 1
	v_permlane32_swap_b32_e32 v138, v140
	v_permlane32_swap_b32_e32 v139, v141
	v_permlane32_swap_b32_e32 v142, v144
	v_permlane32_swap_b32_e32 v143, v145
	global_store_dwordx4 v186, v[138:141], s[22:23] offset:64
	global_store_dwordx4 v186, v[142:145], s[22:23] offset:96
	v_cvt_pk_bf16_f32 v146, v32, v33
	v_cvt_pk_bf16_f32 v147, v34, v35
	v_cvt_pk_bf16_f32 v148, v36, v37
	v_cvt_pk_bf16_f32 v149, v38, v39
	v_cvt_pk_bf16_f32 v150, v40, v41
	v_cvt_pk_bf16_f32 v151, v42, v43
	v_cvt_pk_bf16_f32 v152, v44, v45
	v_cvt_pk_bf16_f32 v153, v46, v47
	s_nop 1
	v_permlane32_swap_b32_e32 v146, v148
	v_permlane32_swap_b32_e32 v147, v149
	v_permlane32_swap_b32_e32 v150, v152
	v_permlane32_swap_b32_e32 v151, v153
	global_store_dwordx4 v186, v[146:149], s[22:23] offset:128
	global_store_dwordx4 v186, v[150:153], s[22:23] offset:160
	v_cvt_pk_bf16_f32 v154, v48, v49
	v_cvt_pk_bf16_f32 v155, v50, v51
; template <int EPI> ...
;     ...
;     } else if (EPI == EPI_RES) {
; #pragma unroll
;       for (int i = 0; i < 16; i++) {
;         const int rl = rbase + (i & 3) + 8 * (i >> 2);
;         const int row = m0 + rl;
;         float v0 = acc0[i], v1 = acc1[i];
;         xf[(size_t)row * 1024 + c0] = v0;
;         xf[(size_t)row * 1024 + c1] = v1;
;         outb[(size_t)row * 1024 + c0] = f2bf(v0);
;         outb[(size_t)row * 1024 + c1] = f2bf(v1);
;         float s = hsum32(v0 * v0 + v1 * v1);
;         if ((lane & 31) == 0) part[(size_t)row * 16 + nt * 2 + wn] = s;
	v_cvt_pk_bf16_f32 v156, v52, v53
	v_cvt_pk_bf16_f32 v157, v54, v55
	v_cvt_pk_bf16_f32 v158, v56, v57
	v_cvt_pk_bf16_f32 v159, v58, v59
	v_cvt_pk_bf16_f32 v160, v60, v61
	v_cvt_pk_bf16_f32 v161, v62, v63
	s_nop 1
	v_permlane32_swap_b32_e32 v154, v156
	v_permlane32_swap_b32_e32 v155, v157
	v_permlane32_swap_b32_e32 v158, v160
	v_permlane32_swap_b32_e32 v159, v161
	global_store_dwordx4 v186, v[154:157], s[22:23] offset:192
	global_store_dwordx4 v186, v[158:161], s[22:23] offset:224
	v_cvt_pk_bf16_f32 v130, v64, v65
	v_cvt_pk_bf16_f32 v131, v66, v67
	v_cvt_pk_bf16_f32 v132, v68, v69
	v_cvt_pk_bf16_f32 v133, v70, v71
	v_cvt_pk_bf16_f32 v134, v72, v73
	v_cvt_pk_bf16_f32 v135, v74, v75
	v_cvt_pk_bf16_f32 v136, v76, v77
	v_cvt_pk_bf16_f32 v137, v78, v79
	s_nop 1
	v_permlane32_swap_b32_e32 v130, v132
	v_permlane32_swap_b32_e32 v131, v133
	v_permlane32_swap_b32_e32 v134, v136
	v_permlane32_swap_b32_e32 v135, v137
	global_store_dwordx4 v187, v[130:133], s[22:23]
	global_store_dwordx4 v187, v[134:137], s[22:23] offset:32
	v_cvt_pk_bf16_f32 v138, v80, v81
	v_cvt_pk_bf16_f32 v139, v82, v83
	v_cvt_pk_bf16_f32 v140, v84, v85
	v_cvt_pk_bf16_f32 v141, v86, v87
	v_cvt_pk_bf16_f32 v142, v88, v89
	v_cvt_pk_bf16_f32 v143, v90, v91
	v_cvt_pk_bf16_f32 v144, v92, v93
	v_cvt_pk_bf16_f32 v145, v94, v95
	s_nop 1
	v_permlane32_swap_b32_e32 v138, v140
	v_permlane32_swap_b32_e32 v139, v141
	v_permlane32_swap_b32_e32 v142, v144
	v_permlane32_swap_b32_e32 v143, v145
	global_store_dwordx4 v187, v[138:141], s[22:23] offset:64
	global_store_dwordx4 v187, v[142:145], s[22:23] offset:96
	v_cvt_pk_bf16_f32 v146, v96, v97
	v_cvt_pk_bf16_f32 v147, v98, v99
	v_cvt_pk_bf16_f32 v148, v100, v101
	v_cvt_pk_bf16_f32 v149, v102, v103
	v_cvt_pk_bf16_f32 v150, v104, v105
	v_cvt_pk_bf16_f32 v151, v106, v107
	v_cvt_pk_bf16_f32 v152, v108, v109
	v_cvt_pk_bf16_f32 v153, v110, v111
	s_nop 1
	v_permlane32_swap_b32_e32 v146, v148
	v_permlane32_swap_b32_e32 v147, v149
	v_permlane32_swap_b32_e32 v150, v152
	v_permlane32_swap_b32_e32 v151, v153
	global_store_dwordx4 v187, v[146:149], s[22:23] offset:128
	global_store_dwordx4 v187, v[150:153], s[22:23] offset:160
	v_cvt_pk_bf16_f32 v154, v112, v113
	v_cvt_pk_bf16_f32 v155, v114, v115
	v_cvt_pk_bf16_f32 v156, v116, v117
	v_cvt_pk_bf16_f32 v157, v118, v119
	v_cvt_pk_bf16_f32 v158, v120, v121
	v_cvt_pk_bf16_f32 v159, v122, v123
	v_cvt_pk_bf16_f32 v160, v124, v125
	v_cvt_pk_bf16_f32 v161, v126, v127
	s_nop 1
	v_permlane32_swap_b32_e32 v154, v156
	v_permlane32_swap_b32_e32 v155, v157
	v_permlane32_swap_b32_e32 v158, v160
	v_permlane32_swap_b32_e32 v159, v161
	global_store_dwordx4 v187, v[154:157], s[22:23] offset:192
	global_store_dwordx4 v187, v[158:161], s[22:23] offset:224
	v_mov_b32_e32 v192, v198
	s_nop 1
	v_permlane32_swap_b32_e32 v192, v198
	v_add_f32_e32 v198, v198, v192
	v_mov_b32_e32 v193, v199
	s_nop 1
	v_permlane32_swap_b32_e32 v193, v199
	v_add_f32_e32 v199, v199, v193
	v_mov_b32_e32 v190, v198
	v_mov_b32_e32 v191, 0
	global_store_dwordx2 v197, v[190:191], s[14:15]
	s_nop 1
	v_mov_b32_e32 v190, v199
	v_mov_b32_e32 v191, 0
	global_store_dwordx2 v197, v[190:191], s[14:15] offset:2048
	s_nop 1
	v_mov_b64_e32 v[0:1], 0
	v_mov_b64_e32 v[2:3], 0
	v_mov_b64_e32 v[4:5], 0
	v_mov_b64_e32 v[6:7], 0
	v_mov_b64_e32 v[8:9], 0
	v_mov_b64_e32 v[10:11], 0
	v_mov_b64_e32 v[12:13], 0
	v_mov_b64_e32 v[14:15], 0
	v_mov_b64_e32 v[16:17], 0
	v_mov_b64_e32 v[18:19], 0
	v_mov_b64_e32 v[20:21], 0
	v_mov_b64_e32 v[22:23], 0
	v_mov_b64_e32 v[24:25], 0
	v_mov_b64_e32 v[26:27], 0
	v_mov_b64_e32 v[28:29], 0
	v_mov_b64_e32 v[30:31], 0
	v_mov_b64_e32 v[32:33], 0
	v_mov_b64_e32 v[34:35], 0
	v_mov_b64_e32 v[36:37], 0
	v_mov_b64_e32 v[38:39], 0
	v_mov_b64_e32 v[40:41], 0
	v_mov_b64_e32 v[42:43], 0
	v_mov_b64_e32 v[44:45], 0
	v_mov_b64_e32 v[46:47], 0
	v_mov_b64_e32 v[48:49], 0
	v_mov_b64_e32 v[50:51], 0
	v_mov_b64_e32 v[52:53], 0
	v_mov_b64_e32 v[54:55], 0
	v_mov_b64_e32 v[56:57], 0
	v_mov_b64_e32 v[58:59], 0
	v_mov_b64_e32 v[60:61], 0
	v_mov_b64_e32 v[62:63], 0
	v_mov_b64_e32 v[64:65], 0
	v_mov_b64_e32 v[66:67], 0
	v_mov_b64_e32 v[68:69], 0
	v_mov_b64_e32 v[70:71], 0
	v_mov_b64_e32 v[72:73], 0
	v_mov_b64_e32 v[74:75], 0
	v_mov_b64_e32 v[76:77], 0
	v_mov_b64_e32 v[78:79], 0
	v_mov_b64_e32 v[80:81], 0
	v_mov_b64_e32 v[82:83], 0
	v_mov_b64_e32 v[84:85], 0
	v_mov_b64_e32 v[86:87], 0
	v_mov_b64_e32 v[88:89], 0
	v_mov_b64_e32 v[90:91], 0
	v_mov_b64_e32 v[92:93], 0
	v_mov_b64_e32 v[94:95], 0
	v_mov_b64_e32 v[96:97], 0
	v_mov_b64_e32 v[98:99], 0
	v_mov_b64_e32 v[100:101], 0
	v_mov_b64_e32 v[102:103], 0
	v_mov_b64_e32 v[104:105], 0
	v_mov_b64_e32 v[106:107], 0
	v_mov_b64_e32 v[108:109], 0
	v_mov_b64_e32 v[110:111], 0
	v_mov_b64_e32 v[112:113], 0
	v_mov_b64_e32 v[114:115], 0
	v_mov_b64_e32 v[116:117], 0
	v_mov_b64_e32 v[118:119], 0
	v_mov_b64_e32 v[120:121], 0
	v_mov_b64_e32 v[122:123], 0
	v_mov_b64_e32 v[124:125], 0
	v_mov_b64_e32 v[126:127], 0
	v_mov_b64_e32 v[154:155], 0
	v_mov_b64_e32 v[156:157], 0
	v_mov_b64_e32 v[158:159], 0
	v_mov_b64_e32 v[160:161], 0
	v_mov_b64_e32 v[162:163], 0
	v_mov_b64_e32 v[164:165], 0
	v_mov_b64_e32 v[166:167], 0
	v_mov_b64_e32 v[168:169], 0
	v_mov_b64_e32 v[170:171], 0
	v_mov_b64_e32 v[172:173], 0
	v_mov_b64_e32 v[174:175], 0
	v_mov_b64_e32 v[176:177], 0
	s_branch .Lgc_next
; template <int EPI>
; __device__ __forceinline__ void gemm_phase(const Params& p, const u16* __restrict__ A, int lda, const u16* __restrict__ BT, int ldb,
;                            int K, int N, u16* __restrict__ outb, int ldo, int resid_in, int boff) {
;     ...
;     if (EPI == EPI_RES && part_unit) {
;       float* xfp = p.out;
; #pragma unroll
;       for (int i = 0; i < 16; i++) {
;         const int rl = wm * 64 + 4 * (lane >> 5) + (i & 3) + 8 * (i >> 2);
;         float* r0p = xfp + (size_t)(m0 + rl) * 1024;
;         float* r1p = r0p + (size_t)32 * 1024;
;         atomicAdd(r0p + c0, acc00[i]); atomicAdd(r0p + c1, acc01[i]);
;         atomicAdd(r1p + c0, acc10[i]); atomicAdd(r1p + c1, acc11[i]);
;       }
.Lgc_loopN:
	ds_read_b128 v[130:133], v178
	ds_read_b128 v[138:141], v182
	ds_read_b128 v[142:145], v182 offset:4096
	ds_read_b128 v[134:137], v178 offset:4096
	ds_read_b128 v[146:149], v182 offset:8192
	ds_read_b128 v[150:153], v182 offset:12288
	v_mfma_f32_32x32x16_bf16 v[0:15], v[154:157], v[162:165], v[0:15]
	v_mfma_f32_32x32x16_bf16 v[16:31], v[154:157], v[166:169], v[16:31]
	v_mfma_f32_32x32x16_bf16 v[80:95], v[158:161], v[166:169], v[80:95]
	v_mfma_f32_32x32x16_bf16 v[64:79], v[158:161], v[162:165], v[64:79]
	v_mfma_f32_32x32x16_bf16 v[32:47], v[154:157], v[170:173], v[32:47]
	v_mfma_f32_32x32x16_bf16 v[48:63], v[154:157], v[174:177], v[48:63]
	v_mfma_f32_32x32x16_bf16 v[112:127], v[158:161], v[174:177], v[112:127]
	v_mfma_f32_32x32x16_bf16 v[96:111], v[158:161], v[170:173], v[96:111]
	ds_read_b128 v[154:157], v179
	ds_read_b128 v[162:165], v183
	ds_read_b128 v[166:169], v183 offset:4096
	ds_read_b128 v[158:161], v179 offset:4096
	ds_read_b128 v[170:173], v183 offset:8192
	ds_read_b128 v[174:177], v183 offset:12288
	s_waitcnt lgkmcnt(6)
	v_mfma_f32_32x32x16_bf16 v[0:15], v[130:133], v[138:141], v[0:15]
	v_mfma_f32_32x32x16_bf16 v[16:31], v[130:133], v[142:145], v[16:31]
	v_mfma_f32_32x32x16_bf16 v[80:95], v[134:137], v[142:145], v[80:95]
	v_mfma_f32_32x32x16_bf16 v[64:79], v[134:137], v[138:141], v[64:79]
	v_mfma_f32_32x32x16_bf16 v[32:47], v[130:133], v[146:149], v[32:47]
	v_mfma_f32_32x32x16_bf16 v[48:63], v[130:133], v[150:153], v[48:63]
	v_mfma_f32_32x32x16_bf16 v[112:127], v[134:137], v[150:153], v[112:127]
	v_mfma_f32_32x32x16_bf16 v[96:111], v[134:137], v[146:149], v[96:111]
	ds_read_b128 v[130:133], v180
	ds_read_b128 v[138:141], v184
	ds_read_b128 v[142:145], v184 offset:4096
	ds_read_b128 v[134:137], v180 offset:4096
	ds_read_b128 v[146:149], v184 offset:8192
	ds_read_b128 v[150:153], v184 offset:12288
	s_waitcnt lgkmcnt(6)
	v_mfma_f32_32x32x16_bf16 v[0:15], v[154:157], v[162:165], v[0:15]
	v_mfma_f32_32x32x16_bf16 v[16:31], v[154:157], v[166:169], v[16:31]
	v_mfma_f32_32x32x16_bf16 v[80:95], v[158:161], v[166:169], v[80:95]
	v_mfma_f32_32x32x16_bf16 v[64:79], v[158:161], v[162:165], v[64:79]
	v_mfma_f32_32x32x16_bf16 v[32:47], v[154:157], v[170:173], v[32:47]
	v_mfma_f32_32x32x16_bf16 v[48:63], v[154:157], v[174:177], v[48:63]
	v_mfma_f32_32x32x16_bf16 v[112:127], v[158:161], v[174:177], v[112:127]
	v_mfma_f32_32x32x16_bf16 v[96:111], v[158:161], v[170:173], v[96:111]
	ds_read_b128 v[154:157], v181
	ds_read_b128 v[162:165], v185
	ds_read_b128 v[166:169], v185 offset:4096
	ds_read_b128 v[158:161], v181 offset:4096
	ds_read_b128 v[170:173], v185 offset:8192
	ds_read_b128 v[174:177], v185 offset:12288
	s_waitcnt lgkmcnt(6)
	v_mfma_f32_32x32x16_bf16 v[0:15], v[130:133], v[138:141], v[0:15]
	v_add_u32_e32 v178, s31, v178
	v_mfma_f32_32x32x16_bf16 v[16:31], v[130:133], v[142:145], v[16:31]
	v_add_u32_e32 v179, s31, v179
	v_mfma_f32_32x32x16_bf16 v[80:95], v[134:137], v[142:145], v[80:95]
	v_add_u32_e32 v180, s31, v180
	v_mfma_f32_32x32x16_bf16 v[64:79], v[134:137], v[138:141], v[64:79]
	v_add_u32_e32 v181, s31, v181
	v_mfma_f32_32x32x16_bf16 v[32:47], v[130:133], v[146:149], v[32:47]
	v_add_u32_e32 v182, s31, v182
	v_mfma_f32_32x32x16_bf16 v[48:63], v[130:133], v[150:153], v[48:63]
	v_add_u32_e32 v183, s31, v183
	v_mfma_f32_32x32x16_bf16 v[112:127], v[134:137], v[150:153], v[112:127]
	v_add_u32_e32 v184, s31, v184
	v_mfma_f32_32x32x16_bf16 v[96:111], v[134:137], v[146:149], v[96:111]
	v_add_u32_e32 v185, s31, v185
	s_add_u32 s13, s13, 1
	s_cmp_eq_u32 s13, 3
	s_cselect_b32 s13, 0, s13
	s_cmp_eq_u32 s13, 2
	s_cselect_b32 s31, s34, s35
	s_waitcnt lgkmcnt(0)
	s_barrier
	s_sub_u32 s18, s18, 1
	s_cmp_lg_u32 s18, 0
	s_cbranch_scc1 .Lgc_loopN
	v_mfma_f32_32x32x16_bf16 v[0:15], v[154:157], v[162:165], v[0:15]
	v_mfma_f32_32x32x16_bf16 v[16:31], v[154:157], v[166:169], v[16:31]
	v_mfma_f32_32x32x16_bf16 v[80:95], v[158:161], v[166:169], v[80:95]
	v_mfma_f32_32x32x16_bf16 v[64:79], v[158:161], v[162:165], v[64:79]
	v_mfma_f32_32x32x16_bf16 v[32:47], v[154:157], v[170:173], v[32:47]
	v_mfma_f32_32x32x16_bf16 v[48:63], v[154:157], v[174:177], v[48:63]
	v_mfma_f32_32x32x16_bf16 v[112:127], v[158:161], v[174:177], v[112:127]
	v_mfma_f32_32x32x16_bf16 v[96:111], v[158:161], v[170:173], v[96:111]
	s_lshl_b32 s11, s6, 8
	s_lshl_b32 s12, s4, 6
	s_add_u32 s11, s11, s12
	v_add_u32_e32 v190, s11, v200
	v_sub_u32_e32 v190, v190, v200
	v_lshl_add_u32 v190, v201, 2, v190
	v_lshlrev_b32_e32 v195, 12, v190
	s_lshl_b32 s11, s7, 7
	v_add_u32_e32 v191, s11, v200
	v_lshlrev_b32_e32 v191, 2, v191
	v_add_u32_e32 v195, v195, v191
	v_add_u32_e32 v196, 0x20000, v195
	s_nop 15
	s_mov_b32 s36, s94
	s_mov_b32 s37, s95
	global_atomic_add_f32 v195, v0, s[36:37]
	global_atomic_add_f32 v195, v16, s[36:37] offset:128
	global_atomic_add_f32 v195, v32, s[36:37] offset:256
	global_atomic_add_f32 v195, v48, s[36:37] offset:384
	s_add_u32 s36, s36, 0x1000
	s_addc_u32 s37, s37, 0
	global_atomic_add_f32 v195, v1, s[36:37]
	global_atomic_add_f32 v195, v17, s[36:37] offset:128
	global_atomic_add_f32 v195, v33, s[36:37] offset:256
	global_atomic_add_f32 v195, v49, s[36:37] offset:384
	s_add_u32 s36, s36, 0x1000
	s_addc_u32 s37, s37, 0
	global_atomic_add_f32 v195, v2, s[36:37]
	global_atomic_add_f32 v195, v18, s[36:37] offset:128
	global_atomic_add_f32 v195, v34, s[36:37] offset:256
	global_atomic_add_f32 v195, v50, s[36:37] offset:384
	s_add_u32 s36, s36, 0x1000
	s_addc_u32 s37, s37, 0
	global_atomic_add_f32 v195, v3, s[36:37]
	global_atomic_add_f32 v195, v19, s[36:37] offset:128
	global_atomic_add_f32 v195, v35, s[36:37] offset:256
	global_atomic_add_f32 v195, v51, s[36:37] offset:384
; template <int EPI>
; __device__ __forceinline__ void gemm_phase(const Params& p, const u16* __restrict__ A, int lda, const u16* __restrict__ BT, int ldb,
;                            int K, int N, u16* __restrict__ outb, int ldo, int resid_in, int boff) {
;     ...
;     if (EPI == EPI_RES && part_unit) {
;       float* xfp = p.out;
; #pragma unroll
;       for (int i = 0; i < 16; i++) {
;         const int rl = wm * 64 + 4 * (lane >> 5) + (i & 3) + 8 * (i >> 2);
;         float* r0p = xfp + (size_t)(m0 + rl) * 1024;
;         float* r1p = r0p + (size_t)32 * 1024;
;         atomicAdd(r0p + c0, acc00[i]); atomicAdd(r0p + c1, acc01[i]);
;         atomicAdd(r1p + c0, acc10[i]); atomicAdd(r1p + c1, acc11[i]);
;       }
	s_add_u32 s36, s36, 0x5000
	s_addc_u32 s37, s37, 0
	global_atomic_add_f32 v195, v4, s[36:37]
	global_atomic_add_f32 v195, v20, s[36:37] offset:128
	global_atomic_add_f32 v195, v36, s[36:37] offset:256
	global_atomic_add_f32 v195, v52, s[36:37] offset:384
	s_add_u32 s36, s36, 0x1000
	s_addc_u32 s37, s37, 0
	global_atomic_add_f32 v195, v5, s[36:37]
	global_atomic_add_f32 v195, v21, s[36:37] offset:128
	global_atomic_add_f32 v195, v37, s[36:37] offset:256
	global_atomic_add_f32 v195, v53, s[36:37] offset:384
	s_add_u32 s36, s36, 0x1000
	s_addc_u32 s37, s37, 0
	global_atomic_add_f32 v195, v6, s[36:37]
	global_atomic_add_f32 v195, v22, s[36:37] offset:128
	global_atomic_add_f32 v195, v38, s[36:37] offset:256
	global_atomic_add_f32 v195, v54, s[36:37] offset:384
	s_add_u32 s36, s36, 0x1000
	s_addc_u32 s37, s37, 0
	global_atomic_add_f32 v195, v7, s[36:37]
	global_atomic_add_f32 v195, v23, s[36:37] offset:128
	global_atomic_add_f32 v195, v39, s[36:37] offset:256
	global_atomic_add_f32 v195, v55, s[36:37] offset:384
	s_add_u32 s36, s36, 0x5000
	s_addc_u32 s37, s37, 0
	global_atomic_add_f32 v195, v8, s[36:37]
	global_atomic_add_f32 v195, v24, s[36:37] offset:128
	global_atomic_add_f32 v195, v40, s[36:37] offset:256
	global_atomic_add_f32 v195, v56, s[36:37] offset:384
	s_add_u32 s36, s36, 0x1000
	s_addc_u32 s37, s37, 0
	global_atomic_add_f32 v195, v9, s[36:37]
	global_atomic_add_f32 v195, v25, s[36:37] offset:128
	global_atomic_add_f32 v195, v41, s[36:37] offset:256
	global_atomic_add_f32 v195, v57, s[36:37] offset:384
	s_add_u32 s36, s36, 0x1000
	s_addc_u32 s37, s37, 0
	global_atomic_add_f32 v195, v10, s[36:37]
	global_atomic_add_f32 v195, v26, s[36:37] offset:128
	global_atomic_add_f32 v195, v42, s[36:37] offset:256
	global_atomic_add_f32 v195, v58, s[36:37] offset:384
	s_add_u32 s36, s36, 0x1000
	s_addc_u32 s37, s37, 0
	global_atomic_add_f32 v195, v11, s[36:37]
	global_atomic_add_f32 v195, v27, s[36:37] offset:128
	global_atomic_add_f32 v195, v43, s[36:37] offset:256
	global_atomic_add_f32 v195, v59, s[36:37] offset:384
	s_add_u32 s36, s36, 0x5000
	s_addc_u32 s37, s37, 0
	global_atomic_add_f32 v195, v12, s[36:37]
	global_atomic_add_f32 v195, v28, s[36:37] offset:128
	global_atomic_add_f32 v195, v44, s[36:37] offset:256
	global_atomic_add_f32 v195, v60, s[36:37] offset:384
	s_add_u32 s36, s36, 0x1000
	s_addc_u32 s37, s37, 0
	global_atomic_add_f32 v195, v13, s[36:37]
	global_atomic_add_f32 v195, v29, s[36:37] offset:128
	global_atomic_add_f32 v195, v45, s[36:37] offset:256
	global_atomic_add_f32 v195, v61, s[36:37] offset:384
	s_add_u32 s36, s36, 0x1000
	s_addc_u32 s37, s37, 0
	global_atomic_add_f32 v195, v14, s[36:37]
	global_atomic_add_f32 v195, v30, s[36:37] offset:128
	global_atomic_add_f32 v195, v46, s[36:37] offset:256
	global_atomic_add_f32 v195, v62, s[36:37] offset:384
	s_add_u32 s36, s36, 0x1000
	s_addc_u32 s37, s37, 0
	global_atomic_add_f32 v195, v15, s[36:37]
	global_atomic_add_f32 v195, v31, s[36:37] offset:128
	global_atomic_add_f32 v195, v47, s[36:37] offset:256
	global_atomic_add_f32 v195, v63, s[36:37] offset:384
	s_mov_b32 s36, s94
	s_mov_b32 s37, s95
	global_atomic_add_f32 v196, v64, s[36:37]
	global_atomic_add_f32 v196, v80, s[36:37] offset:128
	global_atomic_add_f32 v196, v96, s[36:37] offset:256
	global_atomic_add_f32 v196, v112, s[36:37] offset:384
	s_add_u32 s36, s36, 0x1000
	s_addc_u32 s37, s37, 0
	global_atomic_add_f32 v196, v65, s[36:37]
	global_atomic_add_f32 v196, v81, s[36:37] offset:128
	global_atomic_add_f32 v196, v97, s[36:37] offset:256
	global_atomic_add_f32 v196, v113, s[36:37] offset:384
	s_add_u32 s36, s36, 0x1000
	s_addc_u32 s37, s37, 0
	global_atomic_add_f32 v196, v66, s[36:37]
	global_atomic_add_f32 v196, v82, s[36:37] offset:128
	global_atomic_add_f32 v196, v98, s[36:37] offset:256
	global_atomic_add_f32 v196, v114, s[36:37] offset:384
	s_add_u32 s36, s36, 0x1000
	s_addc_u32 s37, s37, 0
	global_atomic_add_f32 v196, v67, s[36:37]
	global_atomic_add_f32 v196, v83, s[36:37] offset:128
	global_atomic_add_f32 v196, v99, s[36:37] offset:256
	global_atomic_add_f32 v196, v115, s[36:37] offset:384
	s_add_u32 s36, s36, 0x5000
	s_addc_u32 s37, s37, 0
	global_atomic_add_f32 v196, v68, s[36:37]
	global_atomic_add_f32 v196, v84, s[36:37] offset:128
	global_atomic_add_f32 v196, v100, s[36:37] offset:256
	global_atomic_add_f32 v196, v116, s[36:37] offset:384
	s_add_u32 s36, s36, 0x1000
	s_addc_u32 s37, s37, 0
	global_atomic_add_f32 v196, v69, s[36:37]
	global_atomic_add_f32 v196, v85, s[36:37] offset:128
	global_atomic_add_f32 v196, v101, s[36:37] offset:256
	global_atomic_add_f32 v196, v117, s[36:37] offset:384
	s_add_u32 s36, s36, 0x1000
	s_addc_u32 s37, s37, 0
	global_atomic_add_f32 v196, v70, s[36:37]
	global_atomic_add_f32 v196, v86, s[36:37] offset:128
	global_atomic_add_f32 v196, v102, s[36:37] offset:256
	global_atomic_add_f32 v196, v118, s[36:37] offset:384
	s_add_u32 s36, s36, 0x1000
	s_addc_u32 s37, s37, 0
	global_atomic_add_f32 v196, v71, s[36:37]
	global_atomic_add_f32 v196, v87, s[36:37] offset:128
	global_atomic_add_f32 v196, v103, s[36:37] offset:256
	global_atomic_add_f32 v196, v119, s[36:37] offset:384
	s_add_u32 s36, s36, 0x5000
	s_addc_u32 s37, s37, 0
	global_atomic_add_f32 v196, v72, s[36:37]
	global_atomic_add_f32 v196, v88, s[36:37] offset:128
	global_atomic_add_f32 v196, v104, s[36:37] offset:256
	global_atomic_add_f32 v196, v120, s[36:37] offset:384
	s_add_u32 s36, s36, 0x1000
	s_addc_u32 s37, s37, 0
	global_atomic_add_f32 v196, v73, s[36:37]
	global_atomic_add_f32 v196, v89, s[36:37] offset:128
	global_atomic_add_f32 v196, v105, s[36:37] offset:256
	global_atomic_add_f32 v196, v121, s[36:37] offset:384
; template <int EPI>
; __device__ __forceinline__ void gemm_phase(const Params& p, const u16* __restrict__ A, int lda, const u16* __restrict__ BT, int ldb,
;                            int K, int N, u16* __restrict__ outb, int ldo, int resid_in, int boff) {
;     ...
;   for (int un = bstart; un < units; un += G) {
;     int tl = un, kbeg = 0, KT = KTALL;
;     bool part_unit = false;
;     if (un >= t_full) { const int v = un - t_full; tl = t_full + v / split; KT = KTALL / split; kbeg = (v % split) * KT; part_unit = true; }
;     int mt = tl / NT, nt = tl % NT;
;     if (EPI == EPI_RES && NT == 8 && G == 256 && !part_unit) {
;       const int rr = tl >> 8, bb = tl & 255;
;       const int xx = bb & 7, jj = bb >> 3;
;       mt = rr * 32 + xx * 4 + (jj >> 3);
;       nt = jj & 7;
;     } else if ((EPI == EPI_FF1 || EPI == EPI_SCALE) && G == 256 && (NT == 32 || NT == 16) && tl < (tiles & ~255)) {
;       const int rr = tl >> 8, bb = tl & 255;
;       const int xx = bb & 7, jj = bb >> 3;
;       if (NT == 32) { mt = rr * 8 + (xx >> 2) * 4 + (jj >> 3); nt = (xx & 3) * 8 + (jj & 7); }
;       else { mt = rr * 16 + (xx >> 1) * 4 + (jj >> 3); nt = (xx & 1) * 8 + (jj & 7); }
;     }
;     const int m0 = mt * 256, n0 = nt * 128;
;     const u16* gA = A + (size_t)(m0 + lrow) * lda + lch * 8 + (size_t)kbeg * 64;
;     const u16* gB = BT + (size_t)(n0 + lrow) * ldb + lch * 8 + (size_t)kbeg * 64;
;     ...
;     if (EPI == EPI_RES && part_unit) {
;       float* xfp = p.out;
; #pragma unroll
;       for (int i = 0; i < 16; i++) {
;         const int rl = wm * 64 + 4 * (lane >> 5) + (i & 3) + 8 * (i >> 2);
;         float* r0p = xfp + (size_t)(m0 + rl) * 1024;
;         float* r1p = r0p + (size_t)32 * 1024;
;         atomicAdd(r0p + c0, acc00[i]); atomicAdd(r0p + c1, acc01[i]);
;         atomicAdd(r1p + c0, acc10[i]); atomicAdd(r1p + c1, acc11[i]);
;       }
	s_add_u32 s36, s36, 0x1000
	s_addc_u32 s37, s37, 0
	global_atomic_add_f32 v196, v74, s[36:37]
	global_atomic_add_f32 v196, v90, s[36:37] offset:128
	global_atomic_add_f32 v196, v106, s[36:37] offset:256
	global_atomic_add_f32 v196, v122, s[36:37] offset:384
	s_add_u32 s36, s36, 0x1000
	s_addc_u32 s37, s37, 0
	global_atomic_add_f32 v196, v75, s[36:37]
	global_atomic_add_f32 v196, v91, s[36:37] offset:128
	global_atomic_add_f32 v196, v107, s[36:37] offset:256
	global_atomic_add_f32 v196, v123, s[36:37] offset:384
	s_add_u32 s36, s36, 0x5000
	s_addc_u32 s37, s37, 0
	global_atomic_add_f32 v196, v76, s[36:37]
	global_atomic_add_f32 v196, v92, s[36:37] offset:128
	global_atomic_add_f32 v196, v108, s[36:37] offset:256
	global_atomic_add_f32 v196, v124, s[36:37] offset:384
	s_add_u32 s36, s36, 0x1000
	s_addc_u32 s37, s37, 0
	global_atomic_add_f32 v196, v77, s[36:37]
	global_atomic_add_f32 v196, v93, s[36:37] offset:128
	global_atomic_add_f32 v196, v109, s[36:37] offset:256
	global_atomic_add_f32 v196, v125, s[36:37] offset:384
	s_add_u32 s36, s36, 0x1000
	s_addc_u32 s37, s37, 0
	global_atomic_add_f32 v196, v78, s[36:37]
	global_atomic_add_f32 v196, v94, s[36:37] offset:128
	global_atomic_add_f32 v196, v110, s[36:37] offset:256
	global_atomic_add_f32 v196, v126, s[36:37] offset:384
	s_add_u32 s36, s36, 0x1000
	s_addc_u32 s37, s37, 0
	global_atomic_add_f32 v196, v79, s[36:37]
	global_atomic_add_f32 v196, v95, s[36:37] offset:128
	global_atomic_add_f32 v196, v111, s[36:37] offset:256
	global_atomic_add_f32 v196, v127, s[36:37] offset:384
	s_nop 3
	v_mov_b64_e32 v[0:1], 0
	v_mov_b64_e32 v[2:3], 0
	v_mov_b64_e32 v[4:5], 0
	v_mov_b64_e32 v[6:7], 0
	v_mov_b64_e32 v[8:9], 0
	v_mov_b64_e32 v[10:11], 0
	v_mov_b64_e32 v[12:13], 0
	v_mov_b64_e32 v[14:15], 0
	v_mov_b64_e32 v[16:17], 0
	v_mov_b64_e32 v[18:19], 0
	v_mov_b64_e32 v[20:21], 0
	v_mov_b64_e32 v[22:23], 0
	v_mov_b64_e32 v[24:25], 0
	v_mov_b64_e32 v[26:27], 0
	v_mov_b64_e32 v[28:29], 0
	v_mov_b64_e32 v[30:31], 0
	v_mov_b64_e32 v[32:33], 0
	v_mov_b64_e32 v[34:35], 0
	v_mov_b64_e32 v[36:37], 0
	v_mov_b64_e32 v[38:39], 0
	v_mov_b64_e32 v[40:41], 0
	v_mov_b64_e32 v[42:43], 0
	v_mov_b64_e32 v[44:45], 0
	v_mov_b64_e32 v[46:47], 0
	v_mov_b64_e32 v[48:49], 0
	v_mov_b64_e32 v[50:51], 0
	v_mov_b64_e32 v[52:53], 0
	v_mov_b64_e32 v[54:55], 0
	v_mov_b64_e32 v[56:57], 0
	v_mov_b64_e32 v[58:59], 0
	v_mov_b64_e32 v[60:61], 0
	v_mov_b64_e32 v[62:63], 0
	v_mov_b64_e32 v[64:65], 0
	v_mov_b64_e32 v[66:67], 0
	v_mov_b64_e32 v[68:69], 0
	v_mov_b64_e32 v[70:71], 0
	v_mov_b64_e32 v[72:73], 0
	v_mov_b64_e32 v[74:75], 0
	v_mov_b64_e32 v[76:77], 0
	v_mov_b64_e32 v[78:79], 0
	v_mov_b64_e32 v[80:81], 0
	v_mov_b64_e32 v[82:83], 0
	v_mov_b64_e32 v[84:85], 0
	v_mov_b64_e32 v[86:87], 0
	v_mov_b64_e32 v[88:89], 0
	v_mov_b64_e32 v[90:91], 0
	v_mov_b64_e32 v[92:93], 0
	v_mov_b64_e32 v[94:95], 0
	v_mov_b64_e32 v[96:97], 0
	v_mov_b64_e32 v[98:99], 0
	v_mov_b64_e32 v[100:101], 0
	v_mov_b64_e32 v[102:103], 0
	v_mov_b64_e32 v[104:105], 0
	v_mov_b64_e32 v[106:107], 0
	v_mov_b64_e32 v[108:109], 0
	v_mov_b64_e32 v[110:111], 0
	v_mov_b64_e32 v[112:113], 0
	v_mov_b64_e32 v[114:115], 0
	v_mov_b64_e32 v[116:117], 0
	v_mov_b64_e32 v[118:119], 0
	v_mov_b64_e32 v[120:121], 0
	v_mov_b64_e32 v[122:123], 0
	v_mov_b64_e32 v[124:125], 0
	v_mov_b64_e32 v[126:127], 0
	v_mov_b64_e32 v[154:155], 0
	v_mov_b64_e32 v[156:157], 0
	v_mov_b64_e32 v[158:159], 0
	v_mov_b64_e32 v[160:161], 0
	v_mov_b64_e32 v[162:163], 0
	v_mov_b64_e32 v[164:165], 0
	v_mov_b64_e32 v[166:167], 0
	v_mov_b64_e32 v[168:169], 0
	v_mov_b64_e32 v[170:171], 0
	v_mov_b64_e32 v[172:173], 0
	v_mov_b64_e32 v[174:175], 0
	v_mov_b64_e32 v[176:177], 0
.Lgc_next:
	s_add_u32 s5, s5, s42
	s_cmp_lt_u32 s5, s38
	s_cbranch_scc1 .Lgc_unit
	s_branch .Lgm_exit
.Lgm_producer:
	v_and_b32_e32 v162, 63, v128
	s_sub_u32 s4, s4, 4
	v_and_b32_e32 v160, 7, v162
	v_lshrrev_b32_e32 v161, 4, v162
	v_xor_b32_e32 v163, v160, v161
	v_or_b32_e32 v161, 4, v161
	v_xor_b32_e32 v161, v160, v161
	v_lshlrev_b32_e32 v163, 4, v163
	v_lshlrev_b32_e32 v161, 4, v161
	v_lshrrev_b32_e32 v160, 3, v162
	s_lshl_b32 s6, s4, 6
	v_add_u32_e32 v164, s6, v160
	v_lshlrev_b32_e32 v164, s45, v164
	s_lshl_b32 s7, 8, s45
	v_add_u32_e32 v130, v164, v163
	v_add_u32_e32 v164, s7, v164
	v_add_u32_e32 v131, v164, v161
	v_add_u32_e32 v164, s7, v164
	v_add_u32_e32 v132, v164, v163
	v_add_u32_e32 v164, s7, v164
	v_add_u32_e32 v133, v164, v161
	v_add_u32_e32 v164, s7, v164
	v_add_u32_e32 v134, v164, v163
	v_add_u32_e32 v164, s7, v164
	v_add_u32_e32 v135, v164, v161
	v_add_u32_e32 v164, s7, v164
	v_add_u32_e32 v136, v164, v163
	v_add_u32_e32 v164, s7, v164
	v_add_u32_e32 v137, v164, v161
	s_lshl_b32 s6, s4, 5
	v_add_u32_e32 v164, s6, v160
	v_lshlrev_b32_e32 v164, s46, v164
	s_lshl_b32 s7, 8, s46
	v_add_u32_e32 v138, v164, v163
	v_add_u32_e32 v164, s7, v164
	v_add_u32_e32 v139, v164, v161
	v_add_u32_e32 v164, s7, v164
	v_add_u32_e32 v140, v164, v163
	v_add_u32_e32 v164, s7, v164
	v_add_u32_e32 v141, v164, v161
	s_lshl_b32 s6, s4, 6
	v_add_u32_e32 v165, s6, v162
	v_lshlrev_b32_e32 v164, 2, v165
	v_add_u32_e32 v164, 0x24000, v164
	s_lshl_b32 s32, s4, 13
	s_lshl_b32 s34, s4, 12
	s_add_u32 s34, s34, 0x8000
	s_mov_b32 s31, 0
	s_mov_b32 s33, 0
	s_mov_b32 s12, 0
	s_mov_b32 s10, 0
	s_mov_b32 s35, 0
	s_mov_b32 s36, s5
	s_lshr_b32 s37, s39, s44
.Lgp_cnt:
	s_cmp_ge_u32 s36, s38
	s_cbranch_scc1 .Lgp_cnt_done
	s_cmp_ge_u32 s36, s28
	s_cselect_b32 s13, s37, s39
	s_add_u32 s35, s35, s13
	s_add_u32 s36, s36, s42
	s_branch .Lgp_cnt
.Lgp_cnt_done:
	s_mov_b32 s11, 0
	s_mov_b32 s18, 0
	s_cmp_ge_u32 s5, s38
	s_cbranch_scc1 .Lgp_su_done_p0
	s_cmp_ge_u32 s5, s28
	s_cbranch_scc1 .Lgm_split_p0
	s_mov_b32 s8, 0
	s_mov_b32 s9, s39
	s_mov_b32 s10, 0
	s_cmp_eq_u32 s27, 0
	s_cbranch_scc1 .Lgm_plain_p0
	s_cmp_ge_u32 s5, s29
	s_cbranch_scc1 .Lgm_plain_p0
	s_lshr_b32 s6, s5, 8
	s_and_b32 s7, s5, 0xff
	s_and_b32 s36, s7, 7
	s_lshr_b32 s37, s7, 3
	s_cmp_eq_u32 s27, 3
	s_cbranch_scc1 .Lgm_map8_p0
	s_cmp_eq_u32 s27, 1
	s_cbranch_scc0 .Lgm_map16_p0
	s_lshl_b32 s6, s6, 3
	s_lshr_b32 s7, s36, 2
	s_lshl_b32 s7, s7, 2
	s_add_u32 s6, s6, s7
	s_lshr_b32 s7, s37, 3
	s_add_u32 s6, s6, s7
	s_and_b32 s7, s36, 3
	s_lshl_b32 s7, s7, 3
	s_and_b32 s37, s37, 7
	s_add_u32 s7, s7, s37
	s_branch .Lgm_dec_done_p0

; template <int EPI>
; __device__ __forceinline__ void gemm_phase(const Params& p, const u16* __restrict__ A, int lda, const u16* __restrict__ BT, int ldb,
;                            int K, int N, u16* __restrict__ outb, int ldo, int resid_in, int boff) {
;     ...
;     const int m0 = mt * 256, n0 = nt * 128;
;     const u16* gA = A + (size_t)(m0 + lrow) * lda + lch * 8 + (size_t)kbeg * 64;
;     const u16* gB = BT + (size_t)(n0 + lrow) * ldb + lch * 8 + (size_t)kbeg * 64;
;     uint4 xa0, xa1, xa2, xa3, xb0, xb1;
;     uint4 ya0, ya1, ya2, ya3, yb0, yb1;
;     ...
;     if (EPI == EPI_SCALE || EPI == EPI_FF1) {
;       const float4* pp = (const float4*)(part + (size_t)(m0 + (tid & 255)) * 16);
;       pq0 = pp[0]; pq1 = pp[1]; pq2 = pp[2]; pq3 = pp[3];
;     }
.Lgm_dec_done_p0:
	s_mov_b32 s11, 1
	s_mov_b32 s18, s9
	s_add_u32 s36, s45, 8
	s_lshl_b32 s36, s6, s36
	s_lshl_b32 s37, s8, 7
	s_add_u32 s36, s36, s37
	s_add_u32 s0, s16, s36
	s_addc_u32 s1, s17, 0
	s_add_u32 s36, s46, 7
	s_lshl_b32 s36, s7, s36
	s_add_u32 s36, s36, s37
	s_add_u32 s2, s20, s36
	s_addc_u32 s3, s21, 0
	s_cmp_eq_u32 s30, 3
	s_cbranch_scc1 .Lgp_su_done_p0
	s_mov_b32 s12, 1
	s_lshl_b32 s36, s6, 8
	v_add_u32_e32 v160, s36, v165
	v_lshlrev_b32_e32 v160, 6, v160
.Lgp_su_done_p0:
	s_mov_b32 s10, 0
	s_mov_b32 s19, 0
	s_cmp_eq_u32 s11, 0
	s_cbranch_scc1 .Lgp_is_done_pa
	s_mov_b32 s19, 1
	s_cmp_eq_u32 s12, 0
	s_cbranch_scc1 .Lgp_is_nop_pa
	global_load_dwordx4 v[144:147], v160, s[14:15]
	global_load_dwordx4 v[148:151], v160, s[14:15] offset:16
	global_load_dwordx4 v[152:155], v160, s[14:15] offset:32
	global_load_dwordx4 v[156:159], v160, s[14:15] offset:48
	s_mov_b32 s12, 0
	s_mov_b32 s10, 1
.Lgp_is_nop_pa:
	s_add_u32 m0, s31, s32
	s_nop 0
	global_load_lds_dwordx4 v130, s[0:1]
	s_add_u32 m0, m0, 0x400
	s_nop 0
	global_load_lds_dwordx4 v131, s[0:1]
	s_add_u32 m0, m0, 0x400
	s_nop 0
	global_load_lds_dwordx4 v132, s[0:1]
	s_add_u32 m0, m0, 0x400
	s_nop 0
	global_load_lds_dwordx4 v133, s[0:1]
	s_add_u32 m0, m0, 0x400
	s_nop 0
	global_load_lds_dwordx4 v134, s[0:1]
	s_add_u32 m0, m0, 0x400
	s_nop 0
	global_load_lds_dwordx4 v135, s[0:1]
	s_add_u32 m0, m0, 0x400
	s_nop 0
	global_load_lds_dwordx4 v136, s[0:1]
	s_add_u32 m0, m0, 0x400
	s_nop 0
	global_load_lds_dwordx4 v137, s[0:1]
	s_add_u32 m0, s31, s34
	s_nop 0
	global_load_lds_dwordx4 v138, s[2:3]
	s_add_u32 m0, m0, 0x400
	s_nop 0
	global_load_lds_dwordx4 v139, s[2:3]
	s_add_u32 m0, m0, 0x400
	s_nop 0
	global_load_lds_dwordx4 v140, s[2:3]
	s_add_u32 m0, m0, 0x400
	s_nop 0
	global_load_lds_dwordx4 v141, s[2:3]
	s_add_u32 s0, s0, 0x80
	s_addc_u32 s1, s1, 0
	s_add_u32 s2, s2, 0x80
	s_addc_u32 s3, s3, 0
	s_add_u32 s31, s31, 0xc000
	s_cmp_eq_u32 s31, 0x24000
	s_cselect_b32 s31, 0, s31
	s_sub_u32 s18, s18, 1
	s_cmp_lg_u32 s18, 0
	s_cbranch_scc1 .Lgp_is_done_pa
	s_add_u32 s5, s5, s42
	s_mov_b32 s13, s10
	s_mov_b32 s11, 0
	s_mov_b32 s18, 0
	s_cmp_ge_u32 s5, s38
	s_cbranch_scc1 .Lgp_su_done_pau
	s_cmp_ge_u32 s5, s28
	s_cbranch_scc1 .Lgm_split_pau
	s_mov_b32 s8, 0
	s_mov_b32 s9, s39
	s_mov_b32 s10, 0
	s_cmp_eq_u32 s27, 0
	s_cbranch_scc1 .Lgm_plain_pau
	s_cmp_ge_u32 s5, s29
	s_cbranch_scc1 .Lgm_plain_pau
	s_lshr_b32 s6, s5, 8
	s_and_b32 s7, s5, 0xff
	s_and_b32 s36, s7, 7
	s_lshr_b32 s37, s7, 3
	s_cmp_eq_u32 s27, 3
	s_cbranch_scc1 .Lgm_map8_pau
	s_cmp_eq_u32 s27, 1
	s_cbranch_scc0 .Lgm_map16_pau
	s_lshl_b32 s6, s6, 3
	s_lshr_b32 s7, s36, 2
	s_lshl_b32 s7, s7, 2
	s_add_u32 s6, s6, s7
	s_lshr_b32 s7, s37, 3
	s_add_u32 s6, s6, s7
	s_and_b32 s7, s36, 3
	s_lshl_b32 s7, s7, 3
	s_and_b32 s37, s37, 7
	s_add_u32 s7, s7, s37
	s_branch .Lgm_dec_done_pau

; template <int EPI>
; __device__ __forceinline__ void gemm_phase(const Params& p, const u16* __restrict__ A, int lda, const u16* __restrict__ BT, int ldb,
;                            int K, int N, u16* __restrict__ outb, int ldo, int resid_in, int boff) {
;     ...
;     if (EPI == EPI_SCALE || EPI == EPI_FF1) {
;       const float4* pp = (const float4*)(part + (size_t)(m0 + (tid & 255)) * 16);
;       pq0 = pp[0]; pq1 = pp[1]; pq2 = pp[2]; pq3 = pp[3];
;     }
.Lgp_su_done_pau:
	s_mov_b32 s10, s13
.Lgp_is_done_pa:
	s_mov_b32 s19, 0
	s_cmp_eq_u32 s11, 0
	s_cbranch_scc1 .Lgp_is_done_pb
	s_mov_b32 s19, 1
	s_cmp_eq_u32 s12, 0
	s_cbranch_scc1 .Lgp_is_nop_pb
	global_load_dwordx4 v[144:147], v160, s[14:15]
	global_load_dwordx4 v[148:151], v160, s[14:15] offset:16
	global_load_dwordx4 v[152:155], v160, s[14:15] offset:32
	global_load_dwordx4 v[156:159], v160, s[14:15] offset:48
	s_mov_b32 s12, 0
	s_mov_b32 s10, 1

; #define RAW_BARRIER() do { asm volatile("s_waitcnt lgkmcnt(0)" ::: "memory"); __builtin_amdgcn_s_barrier(); asm volatile("" ::: "memory"); } while (0)
; template <int EPI>
; __device__ __forceinline__ void gemm_phase(const Params& p, const u16* __restrict__ A, int lda, const u16* __restrict__ BT, int ldb,
;                            int K, int N, u16* __restrict__ outb, int ldo, int resid_in, int boff) {
;     ...
;     __syncthreads();
;     WRITEX(0);
;     if (KT > 2) LOADX(2);
;     RAW_BARRIER();
;     for (int kt = 0; kt < KT; kt += 2) {
;       if (kt + 1 < KT) WRITEY(1);
;       if (kt + 3 < KT) LOADY(kt + 3);
;       COMPUTE(0);
;       RAW_BARRIER();
;       if (kt + 1 >= KT) break;
;       if (kt + 2 < KT) WRITEX(0);
;       if (kt + 4 < KT) LOADX(kt + 4);
;       COMPUTE(1);
;       RAW_BARRIER();
.Lgp_is_done_pb:
	s_cmp_eq_u32 s19, 0
	s_cbranch_scc1 .Lgp_w0_pc
	s_waitcnt vmcnt(12)
	s_branch .Lgp_w1_pc

; template <int EPI>
; __device__ __forceinline__ void gemm_phase(const Params& p, const u16* __restrict__ A, int lda, const u16* __restrict__ BT, int ldb,
;                            int K, int N, u16* __restrict__ outb, int ldo, int resid_in, int boff) {
;     ...
;     if (EPI == EPI_SCALE || EPI == EPI_FF1) {
;       if (tid < 256) {
;         const float sq = (pq0.x + pq0.y + pq0.z + pq0.w) + (pq1.x + pq1.y + pq1.z + pq1.w) + (pq2.x + pq2.y + pq2.z + pq2.w) + (pq3.x + pq3.y + pq3.z + pq3.w);
;         sRs[tid] = rsqrtf(sq * (1.0f / 1024.0f) + 1e-6f);
;       }
;       __syncthreads();
.Lgp_w1_pc:
	s_cmp_eq_u32 s10, 0
	s_cbranch_scc1 .Lgp_ns_pc
	v_add_f32_e32 v144, v144, v145
	v_add_f32_e32 v146, v146, v147
	v_add_f32_e32 v144, v144, v146
	v_add_f32_e32 v148, v148, v149
	v_add_f32_e32 v150, v150, v151
	v_add_f32_e32 v148, v148, v150
	v_add_f32_e32 v152, v152, v153
	v_add_f32_e32 v154, v154, v155
	v_add_f32_e32 v152, v152, v154
	v_add_f32_e32 v156, v156, v157
	v_add_f32_e32 v158, v158, v159
	v_add_f32_e32 v156, v156, v158
	v_add_f32_e32 v144, v144, v148
	v_add_f32_e32 v152, v152, v156
	v_add_f32_e32 v144, v144, v152
	v_mov_b32_e32 v145, 0x358637bd
	v_fmamk_f32 v144, v144, 0x3a800000, v145
	v_rsq_f32_e32 v144, v144
	v_add_u32_e32 v161, s33, v164
	s_nop 0
	ds_write_b32 v161, v144
	s_xor_b32 s33, s33, 0x400
	s_mov_b32 s10, 0
	s_waitcnt lgkmcnt(0)

; #define RAW_BARRIER() do { asm volatile("s_waitcnt lgkmcnt(0)" ::: "memory"); __builtin_amdgcn_s_barrier(); asm volatile("" ::: "memory"); } while (0)
; template <int EPI>
; __device__ __forceinline__ void gemm_phase(const Params& p, const u16* __restrict__ A, int lda, const u16* __restrict__ BT, int ldb,
;                            int K, int N, u16* __restrict__ outb, int ldo, int resid_in, int boff) {
;     ...
;     for (int kt = 0; kt < KT; kt += 2) {
;       if (kt + 1 < KT) WRITEY(1);
;       if (kt + 3 < KT) LOADY(kt + 3);
;       COMPUTE(0);
;       RAW_BARRIER();
;       if (kt + 1 >= KT) break;
;       if (kt + 2 < KT) WRITEX(0);
;       if (kt + 4 < KT) LOADX(kt + 4);
;       COMPUTE(1);
;       RAW_BARRIER();
;     }
.Lgp_ns_pw:
	s_barrier
	s_sub_u32 s35, s35, 1
	s_cmp_lg_u32 s35, 0
	s_cbranch_scc1 .Lgp_loop
	s_branch .Lgm_exit
.Lgm_exit:
	v_mov_b32_e32 v190, 0x1c040
	v_mov_b32_e32 v192, s98
	v_mov_b32_e32 v193, s99
	ds_write_b64 v190, v[192:193]
	s_waitcnt lgkmcnt(0)
.Lgm_restore:
	v_readlane_b32 s0, v255, 0
	v_readlane_b32 s1, v255, 1
	v_readlane_b32 s2, v255, 2
	v_readlane_b32 s3, v255, 3
	v_readlane_b32 s4, v255, 4
	v_readlane_b32 s5, v255, 5
	v_readlane_b32 s18, v255, 6
	v_readlane_b32 s19, v255, 7
	v_readlane_b32 s20, v255, 8
	v_readlane_b32 s21, v255, 9
	v_readlane_b32 s22, v255, 10
	v_readlane_b32 s23, v255, 11
	v_readlane_b32 s24, v255, 12
	v_readlane_b32 s25, v255, 13
	v_readlane_b32 s26, v255, 14
	v_readlane_b32 s27, v255, 15
	v_readlane_b32 s28, v255, 16
	v_readlane_b32 s29, v255, 17
	v_readlane_b32 s30, v255, 18
	v_readlane_b32 s31, v255, 19
	v_readlane_b32 s32, v255, 20
	v_readlane_b32 s33, v255, 21
	v_readlane_b32 s34, v255, 22
	v_readlane_b32 s35, v255, 23
	v_readlane_b32 s36, v255, 24
	v_readlane_b32 s37, v255, 25
	v_readlane_b32 s38, v255, 26
	v_readlane_b32 s39, v255, 27
	v_readlane_b32 s44, v255, 28
	v_readlane_b32 s45, v255, 29
	v_readlane_b32 s46, v255, 30
	v_readlane_b32 s47, v255, 31
	v_readlane_b32 s48, v255, 32
	v_readlane_b32 s49, v255, 33
	s_nop 3
	s_cmp_eq_u32 s101, 1
	s_cbranch_scc1 .LBB0_153
	s_cmp_eq_u32 s101, 8
	s_cbranch_scc1 .LBB0_1188
	s_cmp_eq_u32 s101, 10
	s_cbranch_scc1 .LBB0_1306
	s_cmp_eq_u32 s101, 11
	s_cbranch_scc1 .LBB0_1458
	s_cmp_eq_u32 s101, 13
	s_cbranch_scc1 .LBB0_1576
	s_cmp_eq_u32 s101, 16
	s_cbranch_scc1 .LBB0_1962
	s_cmp_eq_u32 s101, 18
	s_cbranch_scc1 .LBB0_2080
	s_branch .LBB0_2232

; #define PH(n, sync_) if (plo <= (n) && (n) <= phi) { if ((n) > plo && (sync_)) { if ((n) == 1) { grid.sync(); xb = xcd_barrier_post((unsigned*)(ws + O_XBAR), (volatile LAS unsigned*)&xb_words); } else xcd_barrier(xb); }
; __global__ void __launch_bounds__(512) mega(Params p, int plo, int phi) {
;     ...
;   PH(11, 1) gemm_phase<EPI_RES>(p, WSB(O_H), 4096, WSB(O_WF20), 4096, 4096, 1024, WSO(O_XB), 1024, 0, 0); PHEND
.LBB0_1357:
	s_mov_b32 s101, 11
	s_branch .Lgm_entry

; #define PH(n, sync_) if (plo <= (n) && (n) <= phi) { if ((n) > plo && (sync_)) { if ((n) == 1) { grid.sync(); xb = xcd_barrier_post((unsigned*)(ws + O_XBAR), (volatile LAS unsigned*)&xb_words); } else xcd_barrier(xb); }
; __global__ void __launch_bounds__(512) mega(Params p, int plo, int phi) {
;     ...
;   PH(16, 1) gemm_phase<EPI_RES>(p, WSB(O_Y), 1024, WSB(O_WOUT1), 1024, 1024, 1024, WSO(O_XB), 1024, 0, 0); PHEND
.LBB0_1861:
	s_mov_b32 s101, 16
	s_branch .Lgm_entry

; #define PH(n, sync_) if (plo <= (n) && (n) <= phi) { if ((n) > plo && (sync_)) { if ((n) == 1) { grid.sync(); xb = xcd_barrier_post((unsigned*)(ws + O_XBAR), (volatile LAS unsigned*)&xb_words); } else xcd_barrier(xb); }
; __global__ void __launch_bounds__(512) mega(Params p, int plo, int phi) {
;     ...
;   PH(19, 1) gemm_phase<EPI_RES>(p, WSB(O_H), 4096, WSB(O_WF21), 4096, 4096, 1024, WSO(O_XB), 1024, 0, 0); PHEND
.LBB0_2131:
	s_mov_b32 s101, 19
	s_branch .Lgm_entry
